# peeled first K iteration of each GEMM tile (first MFMA per accumulator takes C=0) and removed the 128 per-tile accumulator-zeroing v_mov
# speedup vs baseline: 1.0326x; 1.0000x over previous
.LBB0_86:
	v_mov_b64_e32 v[0:1], 0x800
	s_ashr_i32 s7, s6, 31
	v_cmp_lt_i64_e32 vcc, s[8:9], v[0:1]
	s_lshl_b64 s[8:9], s[6:7], 20
	s_add_u32 s8, s23, s8
	s_addc_u32 s9, s24, s9
	s_and_b64 s[10:11], vcc, exec
	s_cselect_b32 s7, s9, s15
	s_cselect_b32 s38, s8, s14
	s_ashr_i32 s5, s4, 31
	s_lshl_b64 s[10:11], s[4:5], 20
	s_add_u32 s10, s25, s10
	s_addc_u32 s11, s26, s11
	s_and_b64 s[18:19], vcc, exec
	s_cselect_b32 s5, s11, s17
	s_cselect_b32 s39, s10, s16
	s_add_u32 s14, s14, 0x80080
	s_addc_u32 s15, s15, 0
	s_add_u32 s40, s16, 0x100
	s_addc_u32 s41, s17, 0
	s_mov_b32 s42, -2
	s_mov_b64 s[48:49], 0x80
	v_add_u32_e32 v220, 0x10000, v183
	s_add_u32 s16, s14, 0xfff80080
	s_addc_u32 s17, s15, -1
	s_add_i32 s43, 0, 0x10000
	ds_read_b128 v[128:131], v220 offset:0
	ds_read_b128 v[132:135], v220 offset:1024
	ds_read_b128 v[136:139], v220 offset:2048
	ds_read_b128 v[140:143], v220 offset:3072
	s_cmp_eq_u32 s42, 28
	s_cselect_b32 s19, s7, s17
	s_cselect_b32 s18, s38, s16
	s_cselect_b32 s17, s5, s41
	s_cselect_b32 s16, s39, s40
	s_add_i32 m0, s28, 0xc000
	ds_read_b128 v[144:147], v185
	ds_read_b128 v[148:151], v185 offset:1024
	ds_read_b128 v[152:155], v185 offset:2048
	ds_read_b128 v[156:159], v185 offset:3072
	ds_read_b128 v[170:173], v185 offset:4096
	ds_read_b128 v[174:177], v185 offset:5120
	ds_read_b128 v[178:181], v185 offset:6144
	ds_read_b128 v[186:189], v185 offset:7168
	global_load_lds_dwordx4 v166, s[14:15]
	s_add_i32 m0, s28, 0xe000
	s_nop 0
	global_load_lds_dwordx4 v168, s[14:15]
	s_waitcnt lgkmcnt(8)
	s_barrier
	s_waitcnt lgkmcnt(0)
	v_mfma_f32_16x16x32_bf16 v[124:127], v[128:131], v[144:147], 0
	v_mfma_f32_16x16x32_bf16 v[120:123], v[136:139], v[144:147], 0
	v_mfma_f32_16x16x32_bf16 v[108:111], v[128:131], v[152:155], 0
	v_mfma_f32_16x16x32_bf16 v[104:107], v[136:139], v[152:155], 0
	v_mfma_f32_16x16x32_bf16 v[92:95], v[128:131], v[170:173], 0
	v_mfma_f32_16x16x32_bf16 v[88:91], v[136:139], v[170:173], 0
	v_mfma_f32_16x16x32_bf16 v[76:79], v[128:131], v[178:181], 0
	v_mfma_f32_16x16x32_bf16 v[72:75], v[136:139], v[178:181], 0
	v_mfma_f32_16x16x32_bf16 v[124:127], v[132:135], v[148:151], v[124:127]
	v_mfma_f32_16x16x32_bf16 v[120:123], v[140:143], v[148:151], v[120:123]
	v_mfma_f32_16x16x32_bf16 v[108:111], v[132:135], v[156:159], v[108:111]
	v_mfma_f32_16x16x32_bf16 v[104:107], v[140:143], v[156:159], v[104:107]
	v_mfma_f32_16x16x32_bf16 v[92:95], v[132:135], v[174:177], v[92:95]
	v_mfma_f32_16x16x32_bf16 v[88:91], v[140:143], v[174:177], v[88:91]
	v_mfma_f32_16x16x32_bf16 v[76:79], v[132:135], v[186:189], v[76:79]
	v_mfma_f32_16x16x32_bf16 v[72:75], v[140:143], v[186:189], v[72:75]
	s_barrier
	s_add_i32 s46, 0, 0x14000
	s_add_i32 s43, s43, s27
	ds_read_b128 v[196:199], v220 offset:16384
	ds_read_b128 v[204:207], v220 offset:17408
	ds_read_b128 v[208:211], v220 offset:18432
	ds_read_b128 v[214:217], v220 offset:19456
	s_mov_b32 m0, s43
	s_nop 0
	global_load_lds_dwordx4 v192, s[16:17]
	s_add_i32 m0, s43, 0x2000
	s_nop 0
	global_load_lds_dwordx4 v164, s[16:17]
	s_barrier
	s_waitcnt lgkmcnt(0)
	v_mfma_f32_16x16x32_bf16 v[116:119], v[196:199], v[144:147], 0
	v_mfma_f32_16x16x32_bf16 v[112:115], v[208:211], v[144:147], 0
	v_mfma_f32_16x16x32_bf16 v[100:103], v[196:199], v[152:155], 0
	v_mfma_f32_16x16x32_bf16 v[96:99], v[208:211], v[152:155], 0
	v_mfma_f32_16x16x32_bf16 v[84:87], v[196:199], v[170:173], 0
	v_mfma_f32_16x16x32_bf16 v[80:83], v[208:211], v[170:173], 0
	v_mfma_f32_16x16x32_bf16 v[68:71], v[196:199], v[178:181], 0
	v_mfma_f32_16x16x32_bf16 v[64:67], v[208:211], v[178:181], 0
	v_mfma_f32_16x16x32_bf16 v[116:119], v[204:207], v[148:151], v[116:119]
	v_mfma_f32_16x16x32_bf16 v[112:115], v[214:217], v[148:151], v[112:115]
	v_mfma_f32_16x16x32_bf16 v[100:103], v[204:207], v[156:159], v[100:103]
	v_mfma_f32_16x16x32_bf16 v[96:99], v[214:217], v[156:159], v[96:99]
	v_mfma_f32_16x16x32_bf16 v[84:87], v[204:207], v[174:177], v[84:87]
	v_mfma_f32_16x16x32_bf16 v[80:83], v[214:217], v[174:177], v[80:83]
	v_mfma_f32_16x16x32_bf16 v[68:71], v[204:207], v[186:189], v[68:71]
	v_mfma_f32_16x16x32_bf16 v[64:67], v[214:217], v[186:189], v[64:67]
	s_mov_b32 m0, s28
	s_add_u32 s48, s18, 0x80
	s_addc_u32 s49, s19, 0
	s_barrier
	ds_read_b128 v[144:147], v185 offset:16384
	ds_read_b128 v[148:151], v185 offset:17408
	ds_read_b128 v[152:155], v185 offset:18432
	ds_read_b128 v[156:159], v185 offset:19456
	ds_read_b128 v[170:173], v185 offset:20480
	ds_read_b128 v[174:177], v185 offset:21504
	ds_read_b128 v[178:181], v185 offset:22528
	ds_read_b128 v[186:189], v185 offset:23552
	global_load_lds_dwordx4 v160, s[18:19]
	s_mov_b32 m0, s29
	s_nop 0
	global_load_lds_dwordx4 v162, s[18:19]
	s_barrier
	s_waitcnt lgkmcnt(0)
	v_mfma_f32_16x16x32_bf16 v[60:63], v[128:131], v[144:147], 0
	v_mfma_f32_16x16x32_bf16 v[56:59], v[136:139], v[144:147], 0
	v_mfma_f32_16x16x32_bf16 v[44:47], v[128:131], v[152:155], 0
	v_mfma_f32_16x16x32_bf16 v[40:43], v[136:139], v[152:155], 0
	v_mfma_f32_16x16x32_bf16 v[28:31], v[128:131], v[170:173], 0
	v_mfma_f32_16x16x32_bf16 v[24:27], v[136:139], v[170:173], 0
	v_mfma_f32_16x16x32_bf16 v[12:15], v[128:131], v[178:181], 0
	v_mfma_f32_16x16x32_bf16 v[8:11], v[136:139], v[178:181], 0
	v_mfma_f32_16x16x32_bf16 v[60:63], v[132:135], v[148:151], v[60:63]
	v_mfma_f32_16x16x32_bf16 v[56:59], v[140:143], v[148:151], v[56:59]
	v_mfma_f32_16x16x32_bf16 v[44:47], v[132:135], v[156:159], v[44:47]
	v_mfma_f32_16x16x32_bf16 v[40:43], v[140:143], v[156:159], v[40:43]
	v_mfma_f32_16x16x32_bf16 v[28:31], v[132:135], v[174:177], v[28:31]
	v_mfma_f32_16x16x32_bf16 v[24:27], v[140:143], v[174:177], v[24:27]
	v_mfma_f32_16x16x32_bf16 v[12:15], v[132:135], v[186:189], v[12:15]
	v_mfma_f32_16x16x32_bf16 v[8:11], v[140:143], v[186:189], v[8:11]
	s_barrier
	s_add_u32 s44, s16, 0x80000
	s_addc_u32 s45, s17, 0
	s_add_i32 s43, s46, s27
	s_mov_b32 m0, s43
	s_nop 0
	global_load_lds_dwordx4 v192, s[44:45]
	s_add_i32 m0, s43, 0x2000
	s_nop 0
	global_load_lds_dwordx4 v164, s[44:45]
	s_waitcnt vmcnt(6)
	s_barrier
	v_mfma_f32_16x16x32_bf16 v[52:55], v[196:199], v[144:147], 0
	v_mfma_f32_16x16x32_bf16 v[48:51], v[208:211], v[144:147], 0
	v_mfma_f32_16x16x32_bf16 v[36:39], v[196:199], v[152:155], 0
	v_mfma_f32_16x16x32_bf16 v[32:35], v[208:211], v[152:155], 0
	v_mfma_f32_16x16x32_bf16 v[20:23], v[196:199], v[170:173], 0
	v_mfma_f32_16x16x32_bf16 v[16:19], v[208:211], v[170:173], 0
	v_mfma_f32_16x16x32_bf16 v[4:7], v[196:199], v[178:181], 0
	v_mfma_f32_16x16x32_bf16 v[0:3], v[208:211], v[178:181], 0
	v_mfma_f32_16x16x32_bf16 v[52:55], v[204:207], v[148:151], v[52:55]
	v_mfma_f32_16x16x32_bf16 v[48:51], v[214:217], v[148:151], v[48:51]
	v_mfma_f32_16x16x32_bf16 v[36:39], v[204:207], v[156:159], v[36:39]
	v_mfma_f32_16x16x32_bf16 v[32:35], v[214:217], v[156:159], v[32:35]
	v_mfma_f32_16x16x32_bf16 v[20:23], v[204:207], v[174:177], v[20:23]
	v_mfma_f32_16x16x32_bf16 v[16:19], v[214:217], v[174:177], v[16:19]
	v_mfma_f32_16x16x32_bf16 v[4:7], v[204:207], v[186:189], v[4:7]
	v_mfma_f32_16x16x32_bf16 v[0:3], v[214:217], v[186:189], v[0:3]
	s_add_i32 s43, 0, 0x18000
	s_barrier
	ds_read_b128 v[128:131], v220 offset:32768
	ds_read_b128 v[132:135], v220 offset:33792
	ds_read_b128 v[136:139], v220 offset:34816
	ds_read_b128 v[140:143], v220 offset:35840
	s_add_u32 s18, s18, 0x80000
	s_addc_u32 s19, s19, 0
	s_mov_b32 m0, s30
	ds_read_b128 v[144:147], v185 offset:32768
	ds_read_b128 v[148:151], v185 offset:33792
	ds_read_b128 v[152:155], v185 offset:34816
	ds_read_b128 v[156:159], v185 offset:35840
	ds_read_b128 v[170:173], v185 offset:36864
	ds_read_b128 v[174:177], v185 offset:37888
	ds_read_b128 v[178:181], v185 offset:38912
	ds_read_b128 v[186:189], v185 offset:39936
	global_load_lds_dwordx4 v160, s[18:19]
	s_mov_b32 m0, s31
	s_nop 0
	global_load_lds_dwordx4 v162, s[18:19]
	s_waitcnt lgkmcnt(8)
	s_barrier
	s_waitcnt lgkmcnt(0)
	v_mfma_f32_16x16x32_bf16 v[124:127], v[128:131], v[144:147], v[124:127]
	v_mfma_f32_16x16x32_bf16 v[120:123], v[136:139], v[144:147], v[120:123]
	v_mfma_f32_16x16x32_bf16 v[108:111], v[128:131], v[152:155], v[108:111]
	v_mfma_f32_16x16x32_bf16 v[104:107], v[136:139], v[152:155], v[104:107]
	v_mfma_f32_16x16x32_bf16 v[92:95], v[128:131], v[170:173], v[92:95]
	v_mfma_f32_16x16x32_bf16 v[88:91], v[136:139], v[170:173], v[88:91]
	v_mfma_f32_16x16x32_bf16 v[76:79], v[128:131], v[178:181], v[76:79]
	v_mfma_f32_16x16x32_bf16 v[72:75], v[136:139], v[178:181], v[72:75]
	v_mfma_f32_16x16x32_bf16 v[124:127], v[132:135], v[148:151], v[124:127]
	v_mfma_f32_16x16x32_bf16 v[120:123], v[140:143], v[148:151], v[120:123]
	v_mfma_f32_16x16x32_bf16 v[108:111], v[132:135], v[156:159], v[108:111]
	v_mfma_f32_16x16x32_bf16 v[104:107], v[140:143], v[156:159], v[104:107]
	v_mfma_f32_16x16x32_bf16 v[92:95], v[132:135], v[174:177], v[92:95]
	v_mfma_f32_16x16x32_bf16 v[88:91], v[140:143], v[174:177], v[88:91]
	v_mfma_f32_16x16x32_bf16 v[76:79], v[132:135], v[186:189], v[76:79]
	v_mfma_f32_16x16x32_bf16 v[72:75], v[140:143], v[186:189], v[72:75]
	s_barrier
	s_add_i32 s18, 0, 0x1c000
	s_add_i32 s19, s43, s27
	s_add_i32 m0, s19, 0xffffff80
	ds_read_b128 v[196:199], v220 offset:49152
	ds_read_b128 v[204:207], v220 offset:50176
	ds_read_b128 v[208:211], v220 offset:51200
	ds_read_b128 v[214:217], v220 offset:52224
	global_load_lds_dwordx4 v192, s[16:17] offset:128
	s_add_i32 m0, s19, 0x1f80
	s_nop 0
	global_load_lds_dwordx4 v164, s[16:17] offset:128
	s_barrier
	s_waitcnt lgkmcnt(0)
	v_mfma_f32_16x16x32_bf16 v[116:119], v[196:199], v[144:147], v[116:119]
	v_mfma_f32_16x16x32_bf16 v[112:115], v[208:211], v[144:147], v[112:115]
	v_mfma_f32_16x16x32_bf16 v[100:103], v[196:199], v[152:155], v[100:103]
	v_mfma_f32_16x16x32_bf16 v[96:99], v[208:211], v[152:155], v[96:99]
	v_mfma_f32_16x16x32_bf16 v[84:87], v[196:199], v[170:173], v[84:87]
	v_mfma_f32_16x16x32_bf16 v[80:83], v[208:211], v[170:173], v[80:83]
	v_mfma_f32_16x16x32_bf16 v[68:71], v[196:199], v[178:181], v[68:71]
	v_mfma_f32_16x16x32_bf16 v[64:67], v[208:211], v[178:181], v[64:67]
	v_mfma_f32_16x16x32_bf16 v[116:119], v[204:207], v[148:151], v[116:119]
	v_mfma_f32_16x16x32_bf16 v[112:115], v[214:217], v[148:151], v[112:115]
	v_mfma_f32_16x16x32_bf16 v[100:103], v[204:207], v[156:159], v[100:103]
	v_mfma_f32_16x16x32_bf16 v[96:99], v[214:217], v[156:159], v[96:99]
	v_mfma_f32_16x16x32_bf16 v[84:87], v[204:207], v[174:177], v[84:87]
	v_mfma_f32_16x16x32_bf16 v[80:83], v[214:217], v[174:177], v[80:83]
	v_mfma_f32_16x16x32_bf16 v[68:71], v[204:207], v[186:189], v[68:71]
	v_mfma_f32_16x16x32_bf16 v[64:67], v[214:217], v[186:189], v[64:67]
	s_mov_b32 m0, s35
	s_barrier
	ds_read_b128 v[144:147], v185 offset:49152
	ds_read_b128 v[148:151], v185 offset:50176
	ds_read_b128 v[152:155], v185 offset:51200
	ds_read_b128 v[156:159], v185 offset:52224
	ds_read_b128 v[170:173], v185 offset:53248
	ds_read_b128 v[174:177], v185 offset:54272
	ds_read_b128 v[178:181], v185 offset:55296
	ds_read_b128 v[186:189], v185 offset:56320
	global_load_lds_dwordx4 v160, s[48:49]
	s_mov_b32 m0, s36
	s_nop 0
	global_load_lds_dwordx4 v162, s[48:49]
	s_barrier
	s_waitcnt lgkmcnt(0)
	v_mfma_f32_16x16x32_bf16 v[60:63], v[128:131], v[144:147], v[60:63]
	v_mfma_f32_16x16x32_bf16 v[56:59], v[136:139], v[144:147], v[56:59]
	v_mfma_f32_16x16x32_bf16 v[44:47], v[128:131], v[152:155], v[44:47]
	v_mfma_f32_16x16x32_bf16 v[40:43], v[136:139], v[152:155], v[40:43]
	v_mfma_f32_16x16x32_bf16 v[28:31], v[128:131], v[170:173], v[28:31]
	v_mfma_f32_16x16x32_bf16 v[24:27], v[136:139], v[170:173], v[24:27]
	v_mfma_f32_16x16x32_bf16 v[12:15], v[128:131], v[178:181], v[12:15]
	v_mfma_f32_16x16x32_bf16 v[8:11], v[136:139], v[178:181], v[8:11]
	v_mfma_f32_16x16x32_bf16 v[60:63], v[132:135], v[148:151], v[60:63]
	v_mfma_f32_16x16x32_bf16 v[56:59], v[140:143], v[148:151], v[56:59]
	v_mfma_f32_16x16x32_bf16 v[44:47], v[132:135], v[156:159], v[44:47]
	v_mfma_f32_16x16x32_bf16 v[40:43], v[140:143], v[156:159], v[40:43]
	v_mfma_f32_16x16x32_bf16 v[28:31], v[132:135], v[174:177], v[28:31]
	v_mfma_f32_16x16x32_bf16 v[24:27], v[140:143], v[174:177], v[24:27]
	v_mfma_f32_16x16x32_bf16 v[12:15], v[132:135], v[186:189], v[12:15]
	v_mfma_f32_16x16x32_bf16 v[8:11], v[140:143], v[186:189], v[8:11]
	s_barrier
	s_add_u32 s16, s16, 0x80080
	s_addc_u32 s17, s17, 0
	s_add_i32 s18, s18, s27
	s_mov_b32 m0, s18
	s_nop 0
	global_load_lds_dwordx4 v192, s[16:17]
	s_add_i32 m0, s18, 0x2000
	s_nop 0
	global_load_lds_dwordx4 v164, s[16:17]
	s_waitcnt vmcnt(6)
	s_barrier
	v_mfma_f32_16x16x32_bf16 v[52:55], v[196:199], v[144:147], v[52:55]
	v_mfma_f32_16x16x32_bf16 v[48:51], v[208:211], v[144:147], v[48:51]
	v_mfma_f32_16x16x32_bf16 v[36:39], v[196:199], v[152:155], v[36:39]
	v_mfma_f32_16x16x32_bf16 v[32:35], v[208:211], v[152:155], v[32:35]
	v_mfma_f32_16x16x32_bf16 v[20:23], v[196:199], v[170:173], v[20:23]
	v_mfma_f32_16x16x32_bf16 v[16:19], v[208:211], v[170:173], v[16:19]
	v_mfma_f32_16x16x32_bf16 v[4:7], v[196:199], v[178:181], v[4:7]
	v_mfma_f32_16x16x32_bf16 v[0:3], v[208:211], v[178:181], v[0:3]
	v_mfma_f32_16x16x32_bf16 v[52:55], v[204:207], v[148:151], v[52:55]
	v_mfma_f32_16x16x32_bf16 v[48:51], v[214:217], v[148:151], v[48:51]
	v_mfma_f32_16x16x32_bf16 v[36:39], v[204:207], v[156:159], v[36:39]
	v_mfma_f32_16x16x32_bf16 v[32:35], v[214:217], v[156:159], v[32:35]
	v_mfma_f32_16x16x32_bf16 v[20:23], v[204:207], v[174:177], v[20:23]
	v_mfma_f32_16x16x32_bf16 v[16:19], v[214:217], v[174:177], v[16:19]
	v_mfma_f32_16x16x32_bf16 v[4:7], v[204:207], v[186:189], v[4:7]
	v_mfma_f32_16x16x32_bf16 v[0:3], v[214:217], v[186:189], v[0:3]
	s_add_i32 s42, s42, 2
	s_add_u32 s14, s14, 0x100
	s_addc_u32 s15, s15, 0
	s_add_u32 s40, s40, 0x100
	s_addc_u32 s41, s41, 0
	s_cmp_gt_u32 s42, 29
	s_barrier

.LBB0_199:
	v_mov_b64_e32 v[0:1], 0x1000
	s_ashr_i32 s9, s8, 31
	v_cmp_lt_i64_e32 vcc, s[10:11], v[0:1]
	s_lshl_b64 s[10:11], s[8:9], 20
	s_add_u32 s10, s23, s10
	s_addc_u32 s11, s24, s11
	s_and_b64 s[12:13], vcc, exec
	s_cselect_b32 s5, s11, s15
	s_cselect_b32 s9, s10, s14
	s_ashr_i32 s7, s6, 31
	s_lshl_b64 s[12:13], s[6:7], 20
	s_add_u32 s12, s25, s12
	s_addc_u32 s13, s26, s13
	s_and_b64 s[18:19], vcc, exec
	s_cselect_b32 s7, s13, s17
	s_cselect_b32 s37, s12, s16
	s_add_u32 s14, s14, 0x80080
	s_addc_u32 s15, s15, 0
	s_add_u32 s38, s16, 0x100
	s_addc_u32 s39, s17, 0
	s_mov_b32 s40, -2
	s_mov_b64 s[48:49], 0x80
	v_add_u32_e32 v222, 0x10000, v238
	s_add_u32 s16, s14, 0xfff80080
	s_addc_u32 s17, s15, -1
	s_add_i32 s41, 0, 0x10000
	ds_read_b128 v[128:131], v222 offset:0
	ds_read_b128 v[132:135], v222 offset:1024
	ds_read_b128 v[136:139], v222 offset:2048
	ds_read_b128 v[140:143], v222 offset:3072
	s_cmp_eq_u32 s40, 28
	s_cselect_b32 s19, s5, s17
	s_cselect_b32 s18, s9, s16
	s_cselect_b32 s17, s7, s39
	s_cselect_b32 s16, s37, s38
	s_add_i32 m0, s28, 0xc000
	ds_read_b128 v[144:147], v240
	ds_read_b128 v[148:151], v240 offset:1024
	ds_read_b128 v[152:155], v240 offset:2048
	ds_read_b128 v[156:159], v240 offset:3072
	ds_read_b128 v[160:163], v240 offset:4096
	ds_read_b128 v[164:167], v240 offset:5120
	ds_read_b128 v[168:171], v240 offset:6144
	ds_read_b128 v[172:175], v240 offset:7168
	global_load_lds_dwordx4 v218, s[14:15]
	s_add_i32 m0, s28, 0xe000
	s_nop 0
	global_load_lds_dwordx4 v220, s[14:15]
	s_waitcnt lgkmcnt(8)
	s_barrier
	s_waitcnt lgkmcnt(0)
	v_mfma_f32_16x16x32_bf16 v[124:127], v[128:131], v[144:147], 0
	v_mfma_f32_16x16x32_bf16 v[120:123], v[136:139], v[144:147], 0
	v_mfma_f32_16x16x32_bf16 v[116:119], v[128:131], v[152:155], 0
	v_mfma_f32_16x16x32_bf16 v[108:111], v[136:139], v[152:155], 0
	v_mfma_f32_16x16x32_bf16 v[100:103], v[128:131], v[160:163], 0
	v_mfma_f32_16x16x32_bf16 v[92:95], v[136:139], v[160:163], 0
	v_mfma_f32_16x16x32_bf16 v[84:87], v[128:131], v[168:171], 0
	v_mfma_f32_16x16x32_bf16 v[76:79], v[136:139], v[168:171], 0
	v_mfma_f32_16x16x32_bf16 v[124:127], v[132:135], v[148:151], v[124:127]
	v_mfma_f32_16x16x32_bf16 v[120:123], v[140:143], v[148:151], v[120:123]
	v_mfma_f32_16x16x32_bf16 v[116:119], v[132:135], v[156:159], v[116:119]
	v_mfma_f32_16x16x32_bf16 v[108:111], v[140:143], v[156:159], v[108:111]
	v_mfma_f32_16x16x32_bf16 v[100:103], v[132:135], v[164:167], v[100:103]
	v_mfma_f32_16x16x32_bf16 v[92:95], v[140:143], v[164:167], v[92:95]
	v_mfma_f32_16x16x32_bf16 v[84:87], v[132:135], v[172:175], v[84:87]
	v_mfma_f32_16x16x32_bf16 v[76:79], v[140:143], v[172:175], v[76:79]
	s_barrier
	s_add_i32 s44, 0, 0x14000
	s_add_i32 s41, s41, s27
	s_mov_b32 m0, s41
	ds_read_b128 v[176:179], v222 offset:16384
	ds_read_b128 v[180:183], v222 offset:17408
	ds_read_b128 v[184:187], v222 offset:18432
	ds_read_b128 v[188:191], v222 offset:19456
	global_load_lds_dwordx4 v206, s[16:17]
	s_add_i32 m0, s41, 0x2000
	s_nop 0
	global_load_lds_dwordx4 v210, s[16:17]
	s_barrier
	s_waitcnt lgkmcnt(0)
	v_mfma_f32_16x16x32_bf16 v[112:115], v[176:179], v[144:147], 0
	v_mfma_f32_16x16x32_bf16 v[104:107], v[184:187], v[144:147], 0
	v_mfma_f32_16x16x32_bf16 v[96:99], v[176:179], v[152:155], 0
	v_mfma_f32_16x16x32_bf16 v[88:91], v[184:187], v[152:155], 0
	v_mfma_f32_16x16x32_bf16 v[80:83], v[176:179], v[160:163], 0
	v_mfma_f32_16x16x32_bf16 v[72:75], v[184:187], v[160:163], 0
	v_mfma_f32_16x16x32_bf16 v[68:71], v[176:179], v[168:171], 0
	v_mfma_f32_16x16x32_bf16 v[64:67], v[184:187], v[168:171], 0
	v_mfma_f32_16x16x32_bf16 v[112:115], v[180:183], v[148:151], v[112:115]
	v_mfma_f32_16x16x32_bf16 v[104:107], v[188:191], v[148:151], v[104:107]
	v_mfma_f32_16x16x32_bf16 v[96:99], v[180:183], v[156:159], v[96:99]
	v_mfma_f32_16x16x32_bf16 v[88:91], v[188:191], v[156:159], v[88:91]
	v_mfma_f32_16x16x32_bf16 v[80:83], v[180:183], v[164:167], v[80:83]
	v_mfma_f32_16x16x32_bf16 v[72:75], v[188:191], v[164:167], v[72:75]
	v_mfma_f32_16x16x32_bf16 v[68:71], v[180:183], v[172:175], v[68:71]
	v_mfma_f32_16x16x32_bf16 v[64:67], v[188:191], v[172:175], v[64:67]
	s_mov_b32 m0, s28
	s_add_u32 s48, s18, 0x80
	s_addc_u32 s49, s19, 0
	s_barrier
	ds_read_b128 v[144:147], v240 offset:16384
	ds_read_b128 v[148:151], v240 offset:17408
	ds_read_b128 v[152:155], v240 offset:18432
	ds_read_b128 v[156:159], v240 offset:19456
	ds_read_b128 v[160:163], v240 offset:20480
	ds_read_b128 v[164:167], v240 offset:21504
	ds_read_b128 v[168:171], v240 offset:22528
	ds_read_b128 v[172:175], v240 offset:23552
	global_load_lds_dwordx4 v204, s[18:19]
	s_mov_b32 m0, s29
	s_nop 0
	global_load_lds_dwordx4 v208, s[18:19]
	s_barrier
	s_waitcnt lgkmcnt(0)
	v_mfma_f32_16x16x32_bf16 v[60:63], v[128:131], v[144:147], 0
	v_mfma_f32_16x16x32_bf16 v[56:59], v[136:139], v[144:147], 0
	v_mfma_f32_16x16x32_bf16 v[52:55], v[128:131], v[152:155], 0
	v_mfma_f32_16x16x32_bf16 v[44:47], v[136:139], v[152:155], 0
	v_mfma_f32_16x16x32_bf16 v[36:39], v[128:131], v[160:163], 0
	v_mfma_f32_16x16x32_bf16 v[28:31], v[136:139], v[160:163], 0
	v_mfma_f32_16x16x32_bf16 v[20:23], v[128:131], v[168:171], 0
	v_mfma_f32_16x16x32_bf16 v[12:15], v[136:139], v[168:171], 0
	v_mfma_f32_16x16x32_bf16 v[60:63], v[132:135], v[148:151], v[60:63]
	v_mfma_f32_16x16x32_bf16 v[56:59], v[140:143], v[148:151], v[56:59]
	v_mfma_f32_16x16x32_bf16 v[52:55], v[132:135], v[156:159], v[52:55]
	v_mfma_f32_16x16x32_bf16 v[44:47], v[140:143], v[156:159], v[44:47]
	v_mfma_f32_16x16x32_bf16 v[36:39], v[132:135], v[164:167], v[36:39]
	v_mfma_f32_16x16x32_bf16 v[28:31], v[140:143], v[164:167], v[28:31]
	v_mfma_f32_16x16x32_bf16 v[20:23], v[132:135], v[172:175], v[20:23]
	v_mfma_f32_16x16x32_bf16 v[12:15], v[140:143], v[172:175], v[12:15]
	s_barrier
	s_add_u32 s42, s16, 0x80000
	s_addc_u32 s43, s17, 0
	s_add_i32 s41, s44, s27
	s_mov_b32 m0, s41
	s_nop 0
	global_load_lds_dwordx4 v206, s[42:43]
	s_add_i32 m0, s41, 0x2000
	s_nop 0
	global_load_lds_dwordx4 v210, s[42:43]
	s_waitcnt vmcnt(6)
	s_barrier
	v_mfma_f32_16x16x32_bf16 v[48:51], v[176:179], v[144:147], 0
	v_mfma_f32_16x16x32_bf16 v[40:43], v[184:187], v[144:147], 0
	v_mfma_f32_16x16x32_bf16 v[32:35], v[176:179], v[152:155], 0
	v_mfma_f32_16x16x32_bf16 v[24:27], v[184:187], v[152:155], 0
	v_mfma_f32_16x16x32_bf16 v[16:19], v[176:179], v[160:163], 0
	v_mfma_f32_16x16x32_bf16 v[8:11], v[184:187], v[160:163], 0
	v_mfma_f32_16x16x32_bf16 v[4:7], v[176:179], v[168:171], 0
	v_mfma_f32_16x16x32_bf16 v[0:3], v[184:187], v[168:171], 0
	v_mfma_f32_16x16x32_bf16 v[48:51], v[180:183], v[148:151], v[48:51]
	v_mfma_f32_16x16x32_bf16 v[40:43], v[188:191], v[148:151], v[40:43]
	v_mfma_f32_16x16x32_bf16 v[32:35], v[180:183], v[156:159], v[32:35]
	v_mfma_f32_16x16x32_bf16 v[24:27], v[188:191], v[156:159], v[24:27]
	v_mfma_f32_16x16x32_bf16 v[16:19], v[180:183], v[164:167], v[16:19]
	v_mfma_f32_16x16x32_bf16 v[8:11], v[188:191], v[164:167], v[8:11]
	v_mfma_f32_16x16x32_bf16 v[4:7], v[180:183], v[172:175], v[4:7]
	v_mfma_f32_16x16x32_bf16 v[0:3], v[188:191], v[172:175], v[0:3]
	s_add_i32 s41, 0, 0x18000
	s_barrier
	ds_read_b128 v[128:131], v222 offset:32768
	ds_read_b128 v[132:135], v222 offset:33792
	ds_read_b128 v[136:139], v222 offset:34816
	ds_read_b128 v[140:143], v222 offset:35840
	s_add_u32 s18, s18, 0x80000
	s_addc_u32 s19, s19, 0
	s_mov_b32 m0, s30
	ds_read_b128 v[144:147], v240 offset:32768
	ds_read_b128 v[148:151], v240 offset:33792
	ds_read_b128 v[152:155], v240 offset:34816
	ds_read_b128 v[156:159], v240 offset:35840
	ds_read_b128 v[160:163], v240 offset:36864
	ds_read_b128 v[164:167], v240 offset:37888
	ds_read_b128 v[168:171], v240 offset:38912
	ds_read_b128 v[172:175], v240 offset:39936
	global_load_lds_dwordx4 v204, s[18:19]
	s_mov_b32 m0, s31
	s_nop 0
	global_load_lds_dwordx4 v208, s[18:19]
	s_waitcnt lgkmcnt(8)
	s_barrier
	s_waitcnt lgkmcnt(0)
	v_mfma_f32_16x16x32_bf16 v[124:127], v[128:131], v[144:147], v[124:127]
	v_mfma_f32_16x16x32_bf16 v[120:123], v[136:139], v[144:147], v[120:123]
	v_mfma_f32_16x16x32_bf16 v[116:119], v[128:131], v[152:155], v[116:119]
	v_mfma_f32_16x16x32_bf16 v[108:111], v[136:139], v[152:155], v[108:111]
	v_mfma_f32_16x16x32_bf16 v[100:103], v[128:131], v[160:163], v[100:103]
	v_mfma_f32_16x16x32_bf16 v[92:95], v[136:139], v[160:163], v[92:95]
	v_mfma_f32_16x16x32_bf16 v[84:87], v[128:131], v[168:171], v[84:87]
	v_mfma_f32_16x16x32_bf16 v[76:79], v[136:139], v[168:171], v[76:79]
	v_mfma_f32_16x16x32_bf16 v[124:127], v[132:135], v[148:151], v[124:127]
	v_mfma_f32_16x16x32_bf16 v[120:123], v[140:143], v[148:151], v[120:123]
	v_mfma_f32_16x16x32_bf16 v[116:119], v[132:135], v[156:159], v[116:119]
	v_mfma_f32_16x16x32_bf16 v[108:111], v[140:143], v[156:159], v[108:111]
	v_mfma_f32_16x16x32_bf16 v[100:103], v[132:135], v[164:167], v[100:103]
	v_mfma_f32_16x16x32_bf16 v[92:95], v[140:143], v[164:167], v[92:95]
	v_mfma_f32_16x16x32_bf16 v[84:87], v[132:135], v[172:175], v[84:87]
	v_mfma_f32_16x16x32_bf16 v[76:79], v[140:143], v[172:175], v[76:79]
	s_barrier
	s_add_i32 s18, 0, 0x1c000
	s_add_i32 s19, s41, s27
	s_add_i32 m0, s19, 0xffffff80
	ds_read_b128 v[176:179], v222 offset:49152
	ds_read_b128 v[180:183], v222 offset:50176
	ds_read_b128 v[184:187], v222 offset:51200
	ds_read_b128 v[188:191], v222 offset:52224
	global_load_lds_dwordx4 v206, s[16:17] offset:128
	s_add_i32 m0, s19, 0x1f80
	s_nop 0
	global_load_lds_dwordx4 v210, s[16:17] offset:128
	s_barrier
	s_waitcnt lgkmcnt(0)
	v_mfma_f32_16x16x32_bf16 v[112:115], v[176:179], v[144:147], v[112:115]
	v_mfma_f32_16x16x32_bf16 v[104:107], v[184:187], v[144:147], v[104:107]
	v_mfma_f32_16x16x32_bf16 v[96:99], v[176:179], v[152:155], v[96:99]
	v_mfma_f32_16x16x32_bf16 v[88:91], v[184:187], v[152:155], v[88:91]
	v_mfma_f32_16x16x32_bf16 v[80:83], v[176:179], v[160:163], v[80:83]
	v_mfma_f32_16x16x32_bf16 v[72:75], v[184:187], v[160:163], v[72:75]
	v_mfma_f32_16x16x32_bf16 v[68:71], v[176:179], v[168:171], v[68:71]
	v_mfma_f32_16x16x32_bf16 v[64:67], v[184:187], v[168:171], v[64:67]
	v_mfma_f32_16x16x32_bf16 v[112:115], v[180:183], v[148:151], v[112:115]
	v_mfma_f32_16x16x32_bf16 v[104:107], v[188:191], v[148:151], v[104:107]
	v_mfma_f32_16x16x32_bf16 v[96:99], v[180:183], v[156:159], v[96:99]
	v_mfma_f32_16x16x32_bf16 v[88:91], v[188:191], v[156:159], v[88:91]
	v_mfma_f32_16x16x32_bf16 v[80:83], v[180:183], v[164:167], v[80:83]
	v_mfma_f32_16x16x32_bf16 v[72:75], v[188:191], v[164:167], v[72:75]
	v_mfma_f32_16x16x32_bf16 v[68:71], v[180:183], v[172:175], v[68:71]
	v_mfma_f32_16x16x32_bf16 v[64:67], v[188:191], v[172:175], v[64:67]
	s_mov_b32 m0, s33
	s_barrier
	ds_read_b128 v[144:147], v240 offset:49152
	ds_read_b128 v[148:151], v240 offset:50176
	ds_read_b128 v[152:155], v240 offset:51200
	ds_read_b128 v[156:159], v240 offset:52224
	ds_read_b128 v[160:163], v240 offset:53248
	ds_read_b128 v[164:167], v240 offset:54272
	ds_read_b128 v[168:171], v240 offset:55296
	ds_read_b128 v[172:175], v240 offset:56320
	global_load_lds_dwordx4 v204, s[48:49]
	s_mov_b32 m0, s34
	s_nop 0
	global_load_lds_dwordx4 v208, s[48:49]
	s_barrier
	s_waitcnt lgkmcnt(0)
	v_mfma_f32_16x16x32_bf16 v[60:63], v[128:131], v[144:147], v[60:63]
	v_mfma_f32_16x16x32_bf16 v[56:59], v[136:139], v[144:147], v[56:59]
	v_mfma_f32_16x16x32_bf16 v[52:55], v[128:131], v[152:155], v[52:55]
	v_mfma_f32_16x16x32_bf16 v[44:47], v[136:139], v[152:155], v[44:47]
	v_mfma_f32_16x16x32_bf16 v[36:39], v[128:131], v[160:163], v[36:39]
	v_mfma_f32_16x16x32_bf16 v[28:31], v[136:139], v[160:163], v[28:31]
	v_mfma_f32_16x16x32_bf16 v[20:23], v[128:131], v[168:171], v[20:23]
	v_mfma_f32_16x16x32_bf16 v[12:15], v[136:139], v[168:171], v[12:15]
	v_mfma_f32_16x16x32_bf16 v[60:63], v[132:135], v[148:151], v[60:63]
	v_mfma_f32_16x16x32_bf16 v[56:59], v[140:143], v[148:151], v[56:59]
	v_mfma_f32_16x16x32_bf16 v[52:55], v[132:135], v[156:159], v[52:55]
	v_mfma_f32_16x16x32_bf16 v[44:47], v[140:143], v[156:159], v[44:47]
	v_mfma_f32_16x16x32_bf16 v[36:39], v[132:135], v[164:167], v[36:39]
	v_mfma_f32_16x16x32_bf16 v[28:31], v[140:143], v[164:167], v[28:31]
	v_mfma_f32_16x16x32_bf16 v[20:23], v[132:135], v[172:175], v[20:23]
	v_mfma_f32_16x16x32_bf16 v[12:15], v[140:143], v[172:175], v[12:15]
	s_barrier
	s_add_u32 s16, s16, 0x80080
	s_addc_u32 s17, s17, 0
	s_add_i32 s18, s18, s27
	s_mov_b32 m0, s18
	s_nop 0
	global_load_lds_dwordx4 v206, s[16:17]
	s_add_i32 m0, s18, 0x2000
	s_nop 0
	global_load_lds_dwordx4 v210, s[16:17]
	s_waitcnt vmcnt(6)
	s_barrier
	v_mfma_f32_16x16x32_bf16 v[48:51], v[176:179], v[144:147], v[48:51]
	v_mfma_f32_16x16x32_bf16 v[40:43], v[184:187], v[144:147], v[40:43]
	v_mfma_f32_16x16x32_bf16 v[32:35], v[176:179], v[152:155], v[32:35]
	v_mfma_f32_16x16x32_bf16 v[24:27], v[184:187], v[152:155], v[24:27]
	v_mfma_f32_16x16x32_bf16 v[16:19], v[176:179], v[160:163], v[16:19]
	v_mfma_f32_16x16x32_bf16 v[8:11], v[184:187], v[160:163], v[8:11]
	v_mfma_f32_16x16x32_bf16 v[4:7], v[176:179], v[168:171], v[4:7]
	v_mfma_f32_16x16x32_bf16 v[0:3], v[184:187], v[168:171], v[0:3]
	v_mfma_f32_16x16x32_bf16 v[48:51], v[180:183], v[148:151], v[48:51]
	v_mfma_f32_16x16x32_bf16 v[40:43], v[188:191], v[148:151], v[40:43]
	v_mfma_f32_16x16x32_bf16 v[32:35], v[180:183], v[156:159], v[32:35]
	v_mfma_f32_16x16x32_bf16 v[24:27], v[188:191], v[156:159], v[24:27]
	v_mfma_f32_16x16x32_bf16 v[16:19], v[180:183], v[164:167], v[16:19]
	v_mfma_f32_16x16x32_bf16 v[8:11], v[188:191], v[164:167], v[8:11]
	v_mfma_f32_16x16x32_bf16 v[4:7], v[180:183], v[172:175], v[4:7]
	v_mfma_f32_16x16x32_bf16 v[0:3], v[188:191], v[172:175], v[0:3]
	s_add_i32 s40, s40, 2
	s_add_u32 s14, s14, 0x100
	s_addc_u32 s15, s15, 0
	s_add_u32 s38, s38, 0x100
	s_addc_u32 s39, s39, 0
	s_cmp_gt_u32 s40, 29
	s_barrier

.LBB0_216:
	v_mov_b64_e32 v[0:1], 0x1600
	s_ashr_i32 s7, s6, 31
	v_cmp_lt_i64_e32 vcc, s[8:9], v[0:1]
	s_lshl_b64 s[8:9], s[6:7], 20
	s_add_u32 s8, s22, s8
	s_addc_u32 s9, s23, s9
	s_and_b64 s[10:11], vcc, exec
	s_cselect_b32 s7, s9, s15
	s_cselect_b32 s36, s8, s14
	s_ashr_i32 s5, s4, 31
	s_lshl_b64 s[10:11], s[4:5], 20
	s_add_u32 s10, s24, s10
	s_addc_u32 s11, s25, s11
	s_and_b64 s[18:19], vcc, exec
	s_cselect_b32 s5, s11, s17
	s_cselect_b32 s37, s10, s16
	s_add_u32 s14, s14, 0x80080
	s_addc_u32 s15, s15, 0
	s_add_u32 s38, s16, 0x100
	s_addc_u32 s39, s17, 0
	s_mov_b32 s40, -2
	s_mov_b64 s[48:49], 0x80
	v_add_u32_e32 v220, 0x10000, v141
	s_add_u32 s16, s14, 0xfff80080
	s_addc_u32 s17, s15, -1
	s_add_i32 s41, 0, 0x10000
	ds_read_b128 v[144:147], v220 offset:0
	ds_read_b128 v[148:151], v220 offset:1024
	ds_read_b128 v[152:155], v220 offset:2048
	ds_read_b128 v[156:159], v220 offset:3072
	s_cmp_eq_u32 s40, 28
	s_cselect_b32 s19, s7, s17
	s_cselect_b32 s18, s36, s16
	s_cselect_b32 s17, s5, s39
	s_cselect_b32 s16, s37, s38
	s_add_i32 m0, s13, 0xc000
	ds_read_b128 v[160:163], v143
	ds_read_b128 v[164:167], v143 offset:1024
	ds_read_b128 v[168:171], v143 offset:2048
	ds_read_b128 v[172:175], v143 offset:3072
	ds_read_b128 v[176:179], v143 offset:4096
	ds_read_b128 v[180:183], v143 offset:5120
	ds_read_b128 v[184:187], v143 offset:6144
	ds_read_b128 v[188:191], v143 offset:7168
	global_load_lds_dwordx4 v134, s[14:15]
	s_add_i32 m0, s13, 0xe000
	s_nop 0
	global_load_lds_dwordx4 v136, s[14:15]
	s_waitcnt lgkmcnt(8)
	s_barrier
	s_waitcnt lgkmcnt(0)
	v_mfma_f32_16x16x32_bf16 v[124:127], v[144:147], v[160:163], 0
	v_mfma_f32_16x16x32_bf16 v[116:119], v[152:155], v[160:163], 0
	v_mfma_f32_16x16x32_bf16 v[108:111], v[144:147], v[168:171], 0
	v_mfma_f32_16x16x32_bf16 v[100:103], v[152:155], v[168:171], 0
	v_mfma_f32_16x16x32_bf16 v[92:95], v[144:147], v[176:179], 0
	v_mfma_f32_16x16x32_bf16 v[84:87], v[152:155], v[176:179], 0
	v_mfma_f32_16x16x32_bf16 v[76:79], v[144:147], v[184:187], 0
	v_mfma_f32_16x16x32_bf16 v[68:71], v[152:155], v[184:187], 0
	v_mfma_f32_16x16x32_bf16 v[124:127], v[148:151], v[164:167], v[124:127]
	v_mfma_f32_16x16x32_bf16 v[116:119], v[156:159], v[164:167], v[116:119]
	v_mfma_f32_16x16x32_bf16 v[108:111], v[148:151], v[172:175], v[108:111]
	v_mfma_f32_16x16x32_bf16 v[100:103], v[156:159], v[172:175], v[100:103]
	v_mfma_f32_16x16x32_bf16 v[92:95], v[148:151], v[180:183], v[92:95]
	v_mfma_f32_16x16x32_bf16 v[84:87], v[156:159], v[180:183], v[84:87]
	v_mfma_f32_16x16x32_bf16 v[76:79], v[148:151], v[188:191], v[76:79]
	v_mfma_f32_16x16x32_bf16 v[68:71], v[156:159], v[188:191], v[68:71]
	s_barrier
	s_add_i32 s44, 0, 0x14000
	s_add_i32 s41, s41, s26
	ds_read_b128 v[196:199], v220 offset:16384
	ds_read_b128 v[204:207], v220 offset:17408
	ds_read_b128 v[208:211], v220 offset:18432
	ds_read_b128 v[214:217], v220 offset:19456
	s_mov_b32 m0, s41
	s_nop 0
	global_load_lds_dwordx4 v192, s[16:17]
	s_add_i32 m0, s41, 0x2000
	s_nop 0
	global_load_lds_dwordx4 v128, s[16:17]
	s_barrier
	s_waitcnt lgkmcnt(0)
	v_mfma_f32_16x16x32_bf16 v[120:123], v[196:199], v[160:163], 0
	v_mfma_f32_16x16x32_bf16 v[112:115], v[208:211], v[160:163], 0
	v_mfma_f32_16x16x32_bf16 v[104:107], v[196:199], v[168:171], 0
	v_mfma_f32_16x16x32_bf16 v[96:99], v[208:211], v[168:171], 0
	v_mfma_f32_16x16x32_bf16 v[88:91], v[196:199], v[176:179], 0
	v_mfma_f32_16x16x32_bf16 v[80:83], v[208:211], v[176:179], 0
	v_mfma_f32_16x16x32_bf16 v[72:75], v[196:199], v[184:187], 0
	v_mfma_f32_16x16x32_bf16 v[64:67], v[208:211], v[184:187], 0
	v_mfma_f32_16x16x32_bf16 v[120:123], v[204:207], v[164:167], v[120:123]
	v_mfma_f32_16x16x32_bf16 v[112:115], v[214:217], v[164:167], v[112:115]
	v_mfma_f32_16x16x32_bf16 v[104:107], v[204:207], v[172:175], v[104:107]
	v_mfma_f32_16x16x32_bf16 v[96:99], v[214:217], v[172:175], v[96:99]
	v_mfma_f32_16x16x32_bf16 v[88:91], v[204:207], v[180:183], v[88:91]
	v_mfma_f32_16x16x32_bf16 v[80:83], v[214:217], v[180:183], v[80:83]
	v_mfma_f32_16x16x32_bf16 v[72:75], v[204:207], v[188:191], v[72:75]
	v_mfma_f32_16x16x32_bf16 v[64:67], v[214:217], v[188:191], v[64:67]
	s_mov_b32 m0, s13
	s_add_u32 s48, s18, 0x80
	s_addc_u32 s49, s19, 0
	s_barrier
	ds_read_b128 v[160:163], v143 offset:16384
	ds_read_b128 v[164:167], v143 offset:17408
	ds_read_b128 v[168:171], v143 offset:18432
	ds_read_b128 v[172:175], v143 offset:19456
	ds_read_b128 v[176:179], v143 offset:20480
	ds_read_b128 v[180:183], v143 offset:21504
	ds_read_b128 v[184:187], v143 offset:22528
	ds_read_b128 v[188:191], v143 offset:23552
	global_load_lds_dwordx4 v132, s[18:19]
	s_mov_b32 m0, s28
	s_nop 0
	global_load_lds_dwordx4 v130, s[18:19]
	s_barrier
	s_waitcnt lgkmcnt(0)
	v_mfma_f32_16x16x32_bf16 v[60:63], v[144:147], v[160:163], 0
	v_mfma_f32_16x16x32_bf16 v[52:55], v[152:155], v[160:163], 0
	v_mfma_f32_16x16x32_bf16 v[44:47], v[144:147], v[168:171], 0
	v_mfma_f32_16x16x32_bf16 v[36:39], v[152:155], v[168:171], 0
	v_mfma_f32_16x16x32_bf16 v[28:31], v[144:147], v[176:179], 0
	v_mfma_f32_16x16x32_bf16 v[20:23], v[152:155], v[176:179], 0
	v_mfma_f32_16x16x32_bf16 v[12:15], v[144:147], v[184:187], 0
	v_mfma_f32_16x16x32_bf16 v[4:7], v[152:155], v[184:187], 0
	v_mfma_f32_16x16x32_bf16 v[60:63], v[148:151], v[164:167], v[60:63]
	v_mfma_f32_16x16x32_bf16 v[52:55], v[156:159], v[164:167], v[52:55]
	v_mfma_f32_16x16x32_bf16 v[44:47], v[148:151], v[172:175], v[44:47]
	v_mfma_f32_16x16x32_bf16 v[36:39], v[156:159], v[172:175], v[36:39]
	v_mfma_f32_16x16x32_bf16 v[28:31], v[148:151], v[180:183], v[28:31]
	v_mfma_f32_16x16x32_bf16 v[20:23], v[156:159], v[180:183], v[20:23]
	v_mfma_f32_16x16x32_bf16 v[12:15], v[148:151], v[188:191], v[12:15]
	v_mfma_f32_16x16x32_bf16 v[4:7], v[156:159], v[188:191], v[4:7]
	s_barrier
	s_add_u32 s42, s16, 0x80000
	s_addc_u32 s43, s17, 0
	s_add_i32 s41, s44, s26
	s_mov_b32 m0, s41
	s_nop 0
	global_load_lds_dwordx4 v192, s[42:43]
	s_add_i32 m0, s41, 0x2000
	s_nop 0
	global_load_lds_dwordx4 v128, s[42:43]
	s_waitcnt vmcnt(6)
	s_barrier
	v_mfma_f32_16x16x32_bf16 v[56:59], v[196:199], v[160:163], 0
	v_mfma_f32_16x16x32_bf16 v[48:51], v[208:211], v[160:163], 0
	v_mfma_f32_16x16x32_bf16 v[40:43], v[196:199], v[168:171], 0
	v_mfma_f32_16x16x32_bf16 v[32:35], v[208:211], v[168:171], 0
	v_mfma_f32_16x16x32_bf16 v[24:27], v[196:199], v[176:179], 0
	v_mfma_f32_16x16x32_bf16 v[16:19], v[208:211], v[176:179], 0
	v_mfma_f32_16x16x32_bf16 v[8:11], v[196:199], v[184:187], 0
	v_mfma_f32_16x16x32_bf16 v[0:3], v[208:211], v[184:187], 0
	v_mfma_f32_16x16x32_bf16 v[56:59], v[204:207], v[164:167], v[56:59]
	v_mfma_f32_16x16x32_bf16 v[48:51], v[214:217], v[164:167], v[48:51]
	v_mfma_f32_16x16x32_bf16 v[40:43], v[204:207], v[172:175], v[40:43]
	v_mfma_f32_16x16x32_bf16 v[32:35], v[214:217], v[172:175], v[32:35]
	v_mfma_f32_16x16x32_bf16 v[24:27], v[204:207], v[180:183], v[24:27]
	v_mfma_f32_16x16x32_bf16 v[16:19], v[214:217], v[180:183], v[16:19]
	v_mfma_f32_16x16x32_bf16 v[8:11], v[204:207], v[188:191], v[8:11]
	v_mfma_f32_16x16x32_bf16 v[0:3], v[214:217], v[188:191], v[0:3]
	s_add_i32 s41, 0, 0x18000
	s_barrier
	ds_read_b128 v[144:147], v220 offset:32768
	ds_read_b128 v[148:151], v220 offset:33792
	ds_read_b128 v[152:155], v220 offset:34816
	ds_read_b128 v[156:159], v220 offset:35840
	s_add_u32 s18, s18, 0x80000
	s_addc_u32 s19, s19, 0
	s_mov_b32 m0, s29
	ds_read_b128 v[160:163], v143 offset:32768
	ds_read_b128 v[164:167], v143 offset:33792
	ds_read_b128 v[168:171], v143 offset:34816
	ds_read_b128 v[172:175], v143 offset:35840
	ds_read_b128 v[176:179], v143 offset:36864
	ds_read_b128 v[180:183], v143 offset:37888
	ds_read_b128 v[184:187], v143 offset:38912
	ds_read_b128 v[188:191], v143 offset:39936
	global_load_lds_dwordx4 v132, s[18:19]
	s_mov_b32 m0, s30
	s_nop 0
	global_load_lds_dwordx4 v130, s[18:19]
	s_waitcnt lgkmcnt(8)
	s_barrier
	s_waitcnt lgkmcnt(0)
	v_mfma_f32_16x16x32_bf16 v[124:127], v[144:147], v[160:163], v[124:127]
	v_mfma_f32_16x16x32_bf16 v[116:119], v[152:155], v[160:163], v[116:119]
	v_mfma_f32_16x16x32_bf16 v[108:111], v[144:147], v[168:171], v[108:111]
	v_mfma_f32_16x16x32_bf16 v[100:103], v[152:155], v[168:171], v[100:103]
	v_mfma_f32_16x16x32_bf16 v[92:95], v[144:147], v[176:179], v[92:95]
	v_mfma_f32_16x16x32_bf16 v[84:87], v[152:155], v[176:179], v[84:87]
	v_mfma_f32_16x16x32_bf16 v[76:79], v[144:147], v[184:187], v[76:79]
	v_mfma_f32_16x16x32_bf16 v[68:71], v[152:155], v[184:187], v[68:71]
	v_mfma_f32_16x16x32_bf16 v[124:127], v[148:151], v[164:167], v[124:127]
	v_mfma_f32_16x16x32_bf16 v[116:119], v[156:159], v[164:167], v[116:119]
	v_mfma_f32_16x16x32_bf16 v[108:111], v[148:151], v[172:175], v[108:111]
	v_mfma_f32_16x16x32_bf16 v[100:103], v[156:159], v[172:175], v[100:103]
	v_mfma_f32_16x16x32_bf16 v[92:95], v[148:151], v[180:183], v[92:95]
	v_mfma_f32_16x16x32_bf16 v[84:87], v[156:159], v[180:183], v[84:87]
	v_mfma_f32_16x16x32_bf16 v[76:79], v[148:151], v[188:191], v[76:79]
	v_mfma_f32_16x16x32_bf16 v[68:71], v[156:159], v[188:191], v[68:71]
	s_barrier
	s_add_i32 s18, 0, 0x1c000
	s_add_i32 s19, s41, s26
	s_add_i32 m0, s19, 0xffffff80
	ds_read_b128 v[196:199], v220 offset:49152
	ds_read_b128 v[204:207], v220 offset:50176
	ds_read_b128 v[208:211], v220 offset:51200
	ds_read_b128 v[214:217], v220 offset:52224
	global_load_lds_dwordx4 v192, s[16:17] offset:128
	s_add_i32 m0, s19, 0x1f80
	s_nop 0
	global_load_lds_dwordx4 v128, s[16:17] offset:128
	s_barrier
	s_waitcnt lgkmcnt(0)
	v_mfma_f32_16x16x32_bf16 v[120:123], v[196:199], v[160:163], v[120:123]
	v_mfma_f32_16x16x32_bf16 v[112:115], v[208:211], v[160:163], v[112:115]
	v_mfma_f32_16x16x32_bf16 v[104:107], v[196:199], v[168:171], v[104:107]
	v_mfma_f32_16x16x32_bf16 v[96:99], v[208:211], v[168:171], v[96:99]
	v_mfma_f32_16x16x32_bf16 v[88:91], v[196:199], v[176:179], v[88:91]
	v_mfma_f32_16x16x32_bf16 v[80:83], v[208:211], v[176:179], v[80:83]
	v_mfma_f32_16x16x32_bf16 v[72:75], v[196:199], v[184:187], v[72:75]
	v_mfma_f32_16x16x32_bf16 v[64:67], v[208:211], v[184:187], v[64:67]
	v_mfma_f32_16x16x32_bf16 v[120:123], v[204:207], v[164:167], v[120:123]
	v_mfma_f32_16x16x32_bf16 v[112:115], v[214:217], v[164:167], v[112:115]
	v_mfma_f32_16x16x32_bf16 v[104:107], v[204:207], v[172:175], v[104:107]
	v_mfma_f32_16x16x32_bf16 v[96:99], v[214:217], v[172:175], v[96:99]
	v_mfma_f32_16x16x32_bf16 v[88:91], v[204:207], v[180:183], v[88:91]
	v_mfma_f32_16x16x32_bf16 v[80:83], v[214:217], v[180:183], v[80:83]
	v_mfma_f32_16x16x32_bf16 v[72:75], v[204:207], v[188:191], v[72:75]
	v_mfma_f32_16x16x32_bf16 v[64:67], v[214:217], v[188:191], v[64:67]
	s_mov_b32 m0, s33
	s_barrier
	ds_read_b128 v[160:163], v143 offset:49152
	ds_read_b128 v[164:167], v143 offset:50176
	ds_read_b128 v[168:171], v143 offset:51200
	ds_read_b128 v[172:175], v143 offset:52224
	ds_read_b128 v[176:179], v143 offset:53248
	ds_read_b128 v[180:183], v143 offset:54272
	ds_read_b128 v[184:187], v143 offset:55296
	ds_read_b128 v[188:191], v143 offset:56320
	global_load_lds_dwordx4 v132, s[48:49]
	s_mov_b32 m0, s34
	s_nop 0
	global_load_lds_dwordx4 v130, s[48:49]
	s_barrier
	s_waitcnt lgkmcnt(0)
	v_mfma_f32_16x16x32_bf16 v[60:63], v[144:147], v[160:163], v[60:63]
	v_mfma_f32_16x16x32_bf16 v[52:55], v[152:155], v[160:163], v[52:55]
	v_mfma_f32_16x16x32_bf16 v[44:47], v[144:147], v[168:171], v[44:47]
	v_mfma_f32_16x16x32_bf16 v[36:39], v[152:155], v[168:171], v[36:39]
	v_mfma_f32_16x16x32_bf16 v[28:31], v[144:147], v[176:179], v[28:31]
	v_mfma_f32_16x16x32_bf16 v[20:23], v[152:155], v[176:179], v[20:23]
	v_mfma_f32_16x16x32_bf16 v[12:15], v[144:147], v[184:187], v[12:15]
	v_mfma_f32_16x16x32_bf16 v[4:7], v[152:155], v[184:187], v[4:7]
	v_mfma_f32_16x16x32_bf16 v[60:63], v[148:151], v[164:167], v[60:63]
	v_mfma_f32_16x16x32_bf16 v[52:55], v[156:159], v[164:167], v[52:55]
	v_mfma_f32_16x16x32_bf16 v[44:47], v[148:151], v[172:175], v[44:47]
	v_mfma_f32_16x16x32_bf16 v[36:39], v[156:159], v[172:175], v[36:39]
	v_mfma_f32_16x16x32_bf16 v[28:31], v[148:151], v[180:183], v[28:31]
	v_mfma_f32_16x16x32_bf16 v[20:23], v[156:159], v[180:183], v[20:23]
	v_mfma_f32_16x16x32_bf16 v[12:15], v[148:151], v[188:191], v[12:15]
	v_mfma_f32_16x16x32_bf16 v[4:7], v[156:159], v[188:191], v[4:7]
	s_barrier
	s_add_u32 s16, s16, 0x80080
	s_addc_u32 s17, s17, 0
	s_add_i32 s18, s18, s26
	s_mov_b32 m0, s18
	s_nop 0
	global_load_lds_dwordx4 v192, s[16:17]
	s_add_i32 m0, s18, 0x2000
	s_nop 0
	global_load_lds_dwordx4 v128, s[16:17]
	s_waitcnt vmcnt(6)
	s_barrier
	v_mfma_f32_16x16x32_bf16 v[56:59], v[196:199], v[160:163], v[56:59]
	v_mfma_f32_16x16x32_bf16 v[48:51], v[208:211], v[160:163], v[48:51]
	v_mfma_f32_16x16x32_bf16 v[40:43], v[196:199], v[168:171], v[40:43]
	v_mfma_f32_16x16x32_bf16 v[32:35], v[208:211], v[168:171], v[32:35]
	v_mfma_f32_16x16x32_bf16 v[24:27], v[196:199], v[176:179], v[24:27]
	v_mfma_f32_16x16x32_bf16 v[16:19], v[208:211], v[176:179], v[16:19]
	v_mfma_f32_16x16x32_bf16 v[8:11], v[196:199], v[184:187], v[8:11]
	v_mfma_f32_16x16x32_bf16 v[0:3], v[208:211], v[184:187], v[0:3]
	v_mfma_f32_16x16x32_bf16 v[56:59], v[204:207], v[164:167], v[56:59]
	v_mfma_f32_16x16x32_bf16 v[48:51], v[214:217], v[164:167], v[48:51]
	v_mfma_f32_16x16x32_bf16 v[40:43], v[204:207], v[172:175], v[40:43]
	v_mfma_f32_16x16x32_bf16 v[32:35], v[214:217], v[172:175], v[32:35]
	v_mfma_f32_16x16x32_bf16 v[24:27], v[204:207], v[180:183], v[24:27]
	v_mfma_f32_16x16x32_bf16 v[16:19], v[214:217], v[180:183], v[16:19]
	v_mfma_f32_16x16x32_bf16 v[8:11], v[204:207], v[188:191], v[8:11]
	v_mfma_f32_16x16x32_bf16 v[0:3], v[214:217], v[188:191], v[0:3]
	s_add_i32 s40, s40, 2
	s_add_u32 s14, s14, 0x100
	s_addc_u32 s15, s15, 0
	s_add_u32 s38, s38, 0x100
	s_addc_u32 s39, s39, 0
	s_cmp_gt_u32 s40, 29
	s_barrier

.LBB0_245:
	s_add_u32 s10, s10, 0x80
	s_addc_u32 s11, s11, 0
	s_add_u32 s42, s12, 0x100
	s_addc_u32 s43, s13, 0
	s_mov_b32 s12, 0
	s_mov_b64 s[48:49], 0x80
	v_readlane_b32 s52, v254, 14
	v_readlane_b32 s53, v254, 15
	v_readlane_b32 s54, v254, 16
	v_readlane_b32 s55, v254, 17
	s_add_i32 s44, s12, 2
	s_add_u32 s14, s10, 0x80
	s_addc_u32 s13, s11, 0
	s_add_i32 s45, 0, 0x10000
	v_add_u32_e32 v132, s45, v191
	ds_read_b128 v[120:123], v132
	ds_read_b128 v[124:127], v132 offset:1024
	ds_read_b128 v[128:131], v132 offset:2048
	ds_read_b128 v[132:135], v132 offset:3072
	s_cmp_eq_u32 s36, s12
	s_cselect_b32 s12, s4, s14
	s_cselect_b32 s13, s5, s13
	s_cselect_b32 s15, s7, s43
	s_cselect_b32 s14, s6, s42
	s_add_i32 m0, s26, 0xc000
	ds_read_b128 v[144:147], v205
	ds_read_b128 v[148:151], v205 offset:1024
	ds_read_b128 v[152:155], v205 offset:2048
	ds_read_b128 v[156:159], v205 offset:3072
	ds_read_b128 v[160:163], v205 offset:4096
	ds_read_b128 v[164:167], v205 offset:5120
	ds_read_b128 v[178:181], v205 offset:6144
	ds_read_b128 v[182:185], v205 offset:7168
	global_load_lds_dwordx4 v174, s[10:11]
	s_add_i32 m0, s26, 0xe000
	s_nop 0
	global_load_lds_dwordx4 v176, s[10:11]
	s_waitcnt lgkmcnt(8)
	s_barrier
	s_waitcnt lgkmcnt(0)
	v_mfma_f32_16x16x32_bf16 v[140:143], v[120:123], v[144:147], 0
	v_mfma_f32_16x16x32_bf16 v[136:139], v[128:131], v[144:147], 0
	v_mfma_f32_16x16x32_bf16 v[108:111], v[120:123], v[152:155], 0
	v_mfma_f32_16x16x32_bf16 v[104:107], v[128:131], v[152:155], 0
	v_mfma_f32_16x16x32_bf16 v[92:95], v[120:123], v[160:163], 0
	v_mfma_f32_16x16x32_bf16 v[88:91], v[128:131], v[160:163], 0
	v_mfma_f32_16x16x32_bf16 v[76:79], v[120:123], v[178:181], 0
	v_mfma_f32_16x16x32_bf16 v[72:75], v[128:131], v[178:181], 0
	v_mfma_f32_16x16x32_bf16 v[140:143], v[124:127], v[148:151], v[140:143]
	v_mfma_f32_16x16x32_bf16 v[136:139], v[132:135], v[148:151], v[136:139]
	v_mfma_f32_16x16x32_bf16 v[108:111], v[124:127], v[156:159], v[108:111]
	v_mfma_f32_16x16x32_bf16 v[104:107], v[132:135], v[156:159], v[104:107]
	v_mfma_f32_16x16x32_bf16 v[92:95], v[124:127], v[164:167], v[92:95]
	v_mfma_f32_16x16x32_bf16 v[88:91], v[132:135], v[164:167], v[88:91]
	v_mfma_f32_16x16x32_bf16 v[76:79], v[124:127], v[182:185], v[76:79]
	v_mfma_f32_16x16x32_bf16 v[72:75], v[132:135], v[182:185], v[72:75]
	s_barrier
	s_add_i32 s46, 0, 0x14000
	v_add_u32_e32 v210, s46, v191
	s_add_i32 s45, s45, s25
	ds_read_b128 v[186:189], v210
	ds_read_b128 v[196:199], v210 offset:1024
	ds_read_b128 v[206:209], v210 offset:2048
	ds_read_b128 v[214:217], v210 offset:3072
	v_lshl_add_u64 v[210:211], s[14:15], 0, v[192:193]
	s_mov_b32 m0, s45
	v_lshl_add_u64 v[218:219], s[14:15], 0, v[172:173]
	global_load_lds_dwordx4 v192, s[14:15]
	s_add_i32 m0, s45, 0x2000
	s_nop 0
	global_load_lds_dwordx4 v172, s[14:15]
	s_barrier
	s_waitcnt lgkmcnt(0)
	v_mfma_f32_16x16x32_bf16 v[116:119], v[186:189], v[144:147], 0
	v_mfma_f32_16x16x32_bf16 v[112:115], v[206:209], v[144:147], 0
	v_mfma_f32_16x16x32_bf16 v[100:103], v[186:189], v[152:155], 0
	v_mfma_f32_16x16x32_bf16 v[96:99], v[206:209], v[152:155], 0
	v_mfma_f32_16x16x32_bf16 v[84:87], v[186:189], v[160:163], 0
	v_mfma_f32_16x16x32_bf16 v[80:83], v[206:209], v[160:163], 0
	v_mfma_f32_16x16x32_bf16 v[68:71], v[186:189], v[178:181], 0
	v_mfma_f32_16x16x32_bf16 v[64:67], v[206:209], v[178:181], 0
	v_mfma_f32_16x16x32_bf16 v[116:119], v[196:199], v[148:151], v[116:119]
	v_mfma_f32_16x16x32_bf16 v[112:115], v[214:217], v[148:151], v[112:115]
	v_mfma_f32_16x16x32_bf16 v[100:103], v[196:199], v[156:159], v[100:103]
	v_mfma_f32_16x16x32_bf16 v[96:99], v[214:217], v[156:159], v[96:99]
	v_mfma_f32_16x16x32_bf16 v[84:87], v[196:199], v[164:167], v[84:87]
	v_mfma_f32_16x16x32_bf16 v[80:83], v[214:217], v[164:167], v[80:83]
	v_mfma_f32_16x16x32_bf16 v[68:71], v[196:199], v[182:185], v[68:71]
	v_mfma_f32_16x16x32_bf16 v[64:67], v[214:217], v[182:185], v[64:67]
	s_mov_b32 m0, s26
	v_lshl_add_u64 v[220:221], s[12:13], 0, v[168:169]
	s_barrier
	ds_read_b128 v[144:147], v205 offset:16384
	ds_read_b128 v[148:151], v205 offset:17408
	ds_read_b128 v[152:155], v205 offset:18432
	ds_read_b128 v[156:159], v205 offset:19456
	ds_read_b128 v[160:163], v205 offset:20480
	ds_read_b128 v[164:167], v205 offset:21504
	ds_read_b128 v[178:181], v205 offset:22528
	ds_read_b128 v[182:185], v205 offset:23552
	global_load_lds_dwordx4 v168, s[12:13]
	v_lshl_add_u64 v[222:223], s[12:13], 0, v[170:171]
	s_mov_b32 m0, s27
	s_nop 0
	global_load_lds_dwordx4 v170, s[12:13]
	s_barrier
	s_waitcnt lgkmcnt(0)
	v_mfma_f32_16x16x32_bf16 v[60:63], v[120:123], v[144:147], 0
	v_mfma_f32_16x16x32_bf16 v[56:59], v[128:131], v[144:147], 0
	v_mfma_f32_16x16x32_bf16 v[44:47], v[120:123], v[152:155], 0
	v_mfma_f32_16x16x32_bf16 v[40:43], v[128:131], v[152:155], 0
	v_mfma_f32_16x16x32_bf16 v[28:31], v[120:123], v[160:163], 0
	v_mfma_f32_16x16x32_bf16 v[24:27], v[128:131], v[160:163], 0
	v_mfma_f32_16x16x32_bf16 v[12:15], v[120:123], v[178:181], 0
	v_mfma_f32_16x16x32_bf16 v[8:11], v[128:131], v[178:181], 0
	v_mfma_f32_16x16x32_bf16 v[60:63], v[124:127], v[148:151], v[60:63]
	v_mfma_f32_16x16x32_bf16 v[56:59], v[132:135], v[148:151], v[56:59]
	v_mfma_f32_16x16x32_bf16 v[44:47], v[124:127], v[156:159], v[44:47]
	v_mfma_f32_16x16x32_bf16 v[40:43], v[132:135], v[156:159], v[40:43]
	v_mfma_f32_16x16x32_bf16 v[28:31], v[124:127], v[164:167], v[28:31]
	v_mfma_f32_16x16x32_bf16 v[24:27], v[132:135], v[164:167], v[24:27]
	v_mfma_f32_16x16x32_bf16 v[12:15], v[124:127], v[182:185], v[12:15]
	v_mfma_f32_16x16x32_bf16 v[8:11], v[132:135], v[182:185], v[8:11]
	s_barrier
	s_add_u32 s14, s14, s52
	s_addc_u32 s15, s15, 0
	s_add_i32 s45, s46, s25
	v_lshl_add_u64 v[224:225], s[14:15], 0, v[192:193]
	s_mov_b32 m0, s45
	v_lshl_add_u64 v[226:227], s[14:15], 0, v[172:173]
	global_load_lds_dwordx4 v192, s[14:15]
	s_add_i32 m0, s45, 0x2000
	s_nop 0
	global_load_lds_dwordx4 v172, s[14:15]
	s_waitcnt vmcnt(6)
	s_barrier
	v_mfma_f32_16x16x32_bf16 v[52:55], v[186:189], v[144:147], 0
	v_mfma_f32_16x16x32_bf16 v[48:51], v[206:209], v[144:147], 0
	v_mfma_f32_16x16x32_bf16 v[36:39], v[186:189], v[152:155], 0
	v_mfma_f32_16x16x32_bf16 v[32:35], v[206:209], v[152:155], 0
	v_mfma_f32_16x16x32_bf16 v[20:23], v[186:189], v[160:163], 0
	v_mfma_f32_16x16x32_bf16 v[16:19], v[206:209], v[160:163], 0
	v_mfma_f32_16x16x32_bf16 v[4:7], v[186:189], v[178:181], 0
	v_mfma_f32_16x16x32_bf16 v[0:3], v[206:209], v[178:181], 0
	v_mfma_f32_16x16x32_bf16 v[52:55], v[196:199], v[148:151], v[52:55]
	v_mfma_f32_16x16x32_bf16 v[48:51], v[214:217], v[148:151], v[48:51]
	v_mfma_f32_16x16x32_bf16 v[36:39], v[196:199], v[156:159], v[36:39]
	v_mfma_f32_16x16x32_bf16 v[32:35], v[214:217], v[156:159], v[32:35]
	v_mfma_f32_16x16x32_bf16 v[20:23], v[196:199], v[164:167], v[20:23]
	v_mfma_f32_16x16x32_bf16 v[16:19], v[214:217], v[164:167], v[16:19]
	v_mfma_f32_16x16x32_bf16 v[4:7], v[196:199], v[182:185], v[4:7]
	v_mfma_f32_16x16x32_bf16 v[0:3], v[214:217], v[182:185], v[0:3]
	s_add_i32 s14, 0, 0x18000
	v_add_u32_e32 v132, s14, v191
	s_barrier
	ds_read_b128 v[120:123], v132
	ds_read_b128 v[124:127], v132 offset:1024
	ds_read_b128 v[128:131], v132 offset:2048
	ds_read_b128 v[132:135], v132 offset:3072
	s_add_u32 s12, s12, s52
	s_addc_u32 s13, s13, 0
	s_mov_b32 m0, s28
	ds_read_b128 v[144:147], v205 offset:32768
	ds_read_b128 v[148:151], v205 offset:33792
	ds_read_b128 v[152:155], v205 offset:34816
	ds_read_b128 v[156:159], v205 offset:35840
	ds_read_b128 v[160:163], v205 offset:36864
	ds_read_b128 v[164:167], v205 offset:37888
	ds_read_b128 v[178:181], v205 offset:38912
	ds_read_b128 v[182:185], v205 offset:39936
	global_load_lds_dwordx4 v168, s[12:13]
	s_mov_b32 m0, s29
	s_nop 0
	global_load_lds_dwordx4 v170, s[12:13]
	s_waitcnt lgkmcnt(8)
	s_barrier
	s_waitcnt lgkmcnt(0)
	v_mfma_f32_16x16x32_bf16 v[140:143], v[120:123], v[144:147], v[140:143]
	v_mfma_f32_16x16x32_bf16 v[136:139], v[128:131], v[144:147], v[136:139]
	v_mfma_f32_16x16x32_bf16 v[108:111], v[120:123], v[152:155], v[108:111]
	v_mfma_f32_16x16x32_bf16 v[104:107], v[128:131], v[152:155], v[104:107]
	v_mfma_f32_16x16x32_bf16 v[92:95], v[120:123], v[160:163], v[92:95]
	v_mfma_f32_16x16x32_bf16 v[88:91], v[128:131], v[160:163], v[88:91]
	v_mfma_f32_16x16x32_bf16 v[76:79], v[120:123], v[178:181], v[76:79]
	v_mfma_f32_16x16x32_bf16 v[72:75], v[128:131], v[178:181], v[72:75]
	v_mfma_f32_16x16x32_bf16 v[140:143], v[124:127], v[148:151], v[140:143]
	v_mfma_f32_16x16x32_bf16 v[136:139], v[132:135], v[148:151], v[136:139]
	v_mfma_f32_16x16x32_bf16 v[108:111], v[124:127], v[156:159], v[108:111]
	v_mfma_f32_16x16x32_bf16 v[104:107], v[132:135], v[156:159], v[104:107]
	v_mfma_f32_16x16x32_bf16 v[92:95], v[124:127], v[164:167], v[92:95]
	v_mfma_f32_16x16x32_bf16 v[88:91], v[132:135], v[164:167], v[88:91]
	v_mfma_f32_16x16x32_bf16 v[76:79], v[124:127], v[182:185], v[76:79]
	v_mfma_f32_16x16x32_bf16 v[72:75], v[132:135], v[182:185], v[72:75]
	s_barrier
	s_add_i32 s12, 0, 0x1c000
	s_add_i32 s13, s14, s25
	v_add_u32_e32 v212, s12, v191
	v_lshl_add_u64 v[210:211], v[210:211], 0, s[48:49]
	s_mov_b32 m0, s13
	ds_read_b128 v[186:189], v212
	ds_read_b128 v[196:199], v212 offset:1024
	ds_read_b128 v[206:209], v212 offset:2048
	ds_read_b128 v[214:217], v212 offset:3072
	global_load_lds_dwordx4 v[210:211], off
	v_lshl_add_u64 v[210:211], v[218:219], 0, s[48:49]
	s_add_i32 m0, s13, 0x2000
	s_nop 0
	global_load_lds_dwordx4 v[210:211], off
	s_barrier
	s_waitcnt lgkmcnt(0)
	v_mfma_f32_16x16x32_bf16 v[116:119], v[186:189], v[144:147], v[116:119]
	v_mfma_f32_16x16x32_bf16 v[112:115], v[206:209], v[144:147], v[112:115]
	v_mfma_f32_16x16x32_bf16 v[100:103], v[186:189], v[152:155], v[100:103]
	v_mfma_f32_16x16x32_bf16 v[96:99], v[206:209], v[152:155], v[96:99]
	v_mfma_f32_16x16x32_bf16 v[84:87], v[186:189], v[160:163], v[84:87]
	v_mfma_f32_16x16x32_bf16 v[80:83], v[206:209], v[160:163], v[80:83]
	v_mfma_f32_16x16x32_bf16 v[68:71], v[186:189], v[178:181], v[68:71]
	v_mfma_f32_16x16x32_bf16 v[64:67], v[206:209], v[178:181], v[64:67]
	v_mfma_f32_16x16x32_bf16 v[116:119], v[196:199], v[148:151], v[116:119]
	v_mfma_f32_16x16x32_bf16 v[112:115], v[214:217], v[148:151], v[112:115]
	v_mfma_f32_16x16x32_bf16 v[100:103], v[196:199], v[156:159], v[100:103]
	v_mfma_f32_16x16x32_bf16 v[96:99], v[214:217], v[156:159], v[96:99]
	v_mfma_f32_16x16x32_bf16 v[84:87], v[196:199], v[164:167], v[84:87]
	v_mfma_f32_16x16x32_bf16 v[80:83], v[214:217], v[164:167], v[80:83]
	v_mfma_f32_16x16x32_bf16 v[68:71], v[196:199], v[182:185], v[68:71]
	v_mfma_f32_16x16x32_bf16 v[64:67], v[214:217], v[182:185], v[64:67]
	s_mov_b32 m0, s34
	v_lshl_add_u64 v[210:211], v[220:221], 0, s[48:49]
	s_barrier
	ds_read_b128 v[144:147], v205 offset:49152
	ds_read_b128 v[148:151], v205 offset:50176
	ds_read_b128 v[152:155], v205 offset:51200
	ds_read_b128 v[156:159], v205 offset:52224
	ds_read_b128 v[160:163], v205 offset:53248
	ds_read_b128 v[164:167], v205 offset:54272
	ds_read_b128 v[178:181], v205 offset:55296
	ds_read_b128 v[182:185], v205 offset:56320
	global_load_lds_dwordx4 v[210:211], off
	v_lshl_add_u64 v[210:211], v[222:223], 0, s[48:49]
	s_mov_b32 m0, s35
	s_nop 0
	global_load_lds_dwordx4 v[210:211], off
	s_barrier
	s_waitcnt lgkmcnt(0)
	v_mfma_f32_16x16x32_bf16 v[60:63], v[120:123], v[144:147], v[60:63]
	v_mfma_f32_16x16x32_bf16 v[56:59], v[128:131], v[144:147], v[56:59]
	v_mfma_f32_16x16x32_bf16 v[44:47], v[120:123], v[152:155], v[44:47]
	v_mfma_f32_16x16x32_bf16 v[40:43], v[128:131], v[152:155], v[40:43]
	v_mfma_f32_16x16x32_bf16 v[28:31], v[120:123], v[160:163], v[28:31]
	v_mfma_f32_16x16x32_bf16 v[24:27], v[128:131], v[160:163], v[24:27]
	v_mfma_f32_16x16x32_bf16 v[12:15], v[120:123], v[178:181], v[12:15]
	v_mfma_f32_16x16x32_bf16 v[8:11], v[128:131], v[178:181], v[8:11]
	v_mfma_f32_16x16x32_bf16 v[60:63], v[124:127], v[148:151], v[60:63]
	v_mfma_f32_16x16x32_bf16 v[56:59], v[132:135], v[148:151], v[56:59]
	v_mfma_f32_16x16x32_bf16 v[44:47], v[124:127], v[156:159], v[44:47]
	v_mfma_f32_16x16x32_bf16 v[40:43], v[132:135], v[156:159], v[40:43]
	v_mfma_f32_16x16x32_bf16 v[28:31], v[124:127], v[164:167], v[28:31]
	v_mfma_f32_16x16x32_bf16 v[24:27], v[132:135], v[164:167], v[24:27]
	v_mfma_f32_16x16x32_bf16 v[12:15], v[124:127], v[182:185], v[12:15]
	v_mfma_f32_16x16x32_bf16 v[8:11], v[132:135], v[182:185], v[8:11]
	s_barrier
	s_add_i32 s12, s12, s25
	v_lshl_add_u64 v[120:121], v[224:225], 0, s[48:49]
	s_mov_b32 m0, s12
	s_nop 0
	global_load_lds_dwordx4 v[120:121], off
	v_lshl_add_u64 v[120:121], v[226:227], 0, s[48:49]
	s_add_i32 m0, s12, 0x2000
	s_nop 0
	global_load_lds_dwordx4 v[120:121], off
	s_waitcnt vmcnt(6)
	s_barrier
	v_mfma_f32_16x16x32_bf16 v[52:55], v[186:189], v[144:147], v[52:55]
	v_mfma_f32_16x16x32_bf16 v[48:51], v[206:209], v[144:147], v[48:51]
	v_mfma_f32_16x16x32_bf16 v[36:39], v[186:189], v[152:155], v[36:39]
	v_mfma_f32_16x16x32_bf16 v[32:35], v[206:209], v[152:155], v[32:35]
	v_mfma_f32_16x16x32_bf16 v[20:23], v[186:189], v[160:163], v[20:23]
	v_mfma_f32_16x16x32_bf16 v[16:19], v[206:209], v[160:163], v[16:19]
	v_mfma_f32_16x16x32_bf16 v[4:7], v[186:189], v[178:181], v[4:7]
	v_mfma_f32_16x16x32_bf16 v[0:3], v[206:209], v[178:181], v[0:3]
	v_mfma_f32_16x16x32_bf16 v[52:55], v[196:199], v[148:151], v[52:55]
	v_mfma_f32_16x16x32_bf16 v[48:51], v[214:217], v[148:151], v[48:51]
	v_mfma_f32_16x16x32_bf16 v[36:39], v[196:199], v[156:159], v[36:39]
	v_mfma_f32_16x16x32_bf16 v[32:35], v[214:217], v[156:159], v[32:35]
	v_mfma_f32_16x16x32_bf16 v[20:23], v[196:199], v[164:167], v[20:23]
	v_mfma_f32_16x16x32_bf16 v[16:19], v[214:217], v[164:167], v[16:19]
	v_mfma_f32_16x16x32_bf16 v[4:7], v[196:199], v[182:185], v[4:7]
	v_mfma_f32_16x16x32_bf16 v[0:3], v[214:217], v[182:185], v[0:3]
	s_add_u32 s10, s10, 0x100
	s_addc_u32 s11, s11, 0
	s_add_u32 s42, s42, 0x100
	s_addc_u32 s43, s43, 0
	s_cmp_ge_u32 s44, s33
	s_mov_b32 s12, s44
	s_barrier

.LBB0_271:
	s_add_u32 s39, s10, 0x100
	s_addc_u32 s40, s11, 0
	s_mov_b32 s41, -2
	s_mov_b64 s[44:45], 0x80
	v_add_u32_e32 v220, 0x10000, v187
	s_add_u32 s10, s8, 0x100
	s_addc_u32 s11, s9, 0
	s_add_i32 s42, 0, 0x10000
	ds_read_b128 v[108:111], v220 offset:0
	ds_read_b128 v[112:115], v220 offset:1024
	ds_read_b128 v[116:119], v220 offset:2048
	ds_read_b128 v[120:123], v220 offset:3072
	s_cmpk_eq_i32 s41, 0x54
	s_cselect_b32 s15, s5, s11
	s_cselect_b32 s14, s4, s10
	s_cselect_b32 s13, s7, s40
	s_cselect_b32 s12, s6, s39
	s_add_i32 m0, s25, 0xc000
	ds_read_b128 v[144:147], v189
	ds_read_b128 v[148:151], v189 offset:1024
	ds_read_b128 v[152:155], v189 offset:2048
	ds_read_b128 v[156:159], v189 offset:3072
	ds_read_b128 v[160:163], v189 offset:4096
	ds_read_b128 v[174:177], v189 offset:5120
	ds_read_b128 v[178:181], v189 offset:6144
	ds_read_b128 v[182:185], v189 offset:7168
	global_load_lds_dwordx4 v170, s[8:9]
	s_add_i32 m0, s25, 0xe000
	s_nop 0
	global_load_lds_dwordx4 v172, s[8:9]
	s_waitcnt lgkmcnt(8)
	s_barrier
	s_waitcnt lgkmcnt(0)
	v_mfma_f32_16x16x32_bf16 v[140:143], v[108:111], v[144:147], 0
	v_mfma_f32_16x16x32_bf16 v[136:139], v[116:119], v[144:147], 0
	v_mfma_f32_16x16x32_bf16 v[132:135], v[108:111], v[152:155], 0
	v_mfma_f32_16x16x32_bf16 v[104:107], v[116:119], v[152:155], 0
	v_mfma_f32_16x16x32_bf16 v[96:99], v[108:111], v[160:163], 0
	v_mfma_f32_16x16x32_bf16 v[88:91], v[116:119], v[160:163], 0
	v_mfma_f32_16x16x32_bf16 v[80:83], v[108:111], v[178:181], 0
	v_mfma_f32_16x16x32_bf16 v[72:75], v[116:119], v[178:181], 0
	v_mfma_f32_16x16x32_bf16 v[140:143], v[112:115], v[148:151], v[140:143]
	v_mfma_f32_16x16x32_bf16 v[136:139], v[120:123], v[148:151], v[136:139]
	v_mfma_f32_16x16x32_bf16 v[132:135], v[112:115], v[156:159], v[132:135]
	v_mfma_f32_16x16x32_bf16 v[104:107], v[120:123], v[156:159], v[104:107]
	v_mfma_f32_16x16x32_bf16 v[96:99], v[112:115], v[174:177], v[96:99]
	v_mfma_f32_16x16x32_bf16 v[88:91], v[120:123], v[174:177], v[88:91]
	v_mfma_f32_16x16x32_bf16 v[80:83], v[112:115], v[182:185], v[80:83]
	v_mfma_f32_16x16x32_bf16 v[72:75], v[120:123], v[182:185], v[72:75]
	s_barrier
	s_add_i32 s43, 0, 0x14000
	s_add_i32 s8, s42, s19
	ds_read_b128 v[196:199], v220 offset:16384
	ds_read_b128 v[204:207], v220 offset:17408
	ds_read_b128 v[208:211], v220 offset:18432
	ds_read_b128 v[214:217], v220 offset:19456
	s_mov_b32 m0, s8
	s_nop 0
	global_load_lds_dwordx4 v192, s[12:13]
	s_add_i32 m0, s8, 0x2000
	s_nop 0
	global_load_lds_dwordx4 v168, s[12:13]
	s_barrier
	s_waitcnt lgkmcnt(0)
	v_mfma_f32_16x16x32_bf16 v[128:131], v[196:199], v[144:147], 0
	v_mfma_f32_16x16x32_bf16 v[124:127], v[208:211], v[144:147], 0
	v_mfma_f32_16x16x32_bf16 v[100:103], v[196:199], v[152:155], 0
	v_mfma_f32_16x16x32_bf16 v[92:95], v[208:211], v[152:155], 0
	v_mfma_f32_16x16x32_bf16 v[84:87], v[196:199], v[160:163], 0
	v_mfma_f32_16x16x32_bf16 v[76:79], v[208:211], v[160:163], 0
	v_mfma_f32_16x16x32_bf16 v[68:71], v[196:199], v[178:181], 0
	v_mfma_f32_16x16x32_bf16 v[64:67], v[208:211], v[178:181], 0
	v_mfma_f32_16x16x32_bf16 v[128:131], v[204:207], v[148:151], v[128:131]
	v_mfma_f32_16x16x32_bf16 v[124:127], v[214:217], v[148:151], v[124:127]
	v_mfma_f32_16x16x32_bf16 v[100:103], v[204:207], v[156:159], v[100:103]
	v_mfma_f32_16x16x32_bf16 v[92:95], v[214:217], v[156:159], v[92:95]
	v_mfma_f32_16x16x32_bf16 v[84:87], v[204:207], v[174:177], v[84:87]
	v_mfma_f32_16x16x32_bf16 v[76:79], v[214:217], v[174:177], v[76:79]
	v_mfma_f32_16x16x32_bf16 v[68:71], v[204:207], v[182:185], v[68:71]
	v_mfma_f32_16x16x32_bf16 v[64:67], v[214:217], v[182:185], v[64:67]
	s_mov_b32 m0, s25
	s_add_u32 s44, s14, 0x80
	s_addc_u32 s45, s15, 0
	s_barrier
	ds_read_b128 v[144:147], v189 offset:16384
	ds_read_b128 v[148:151], v189 offset:17408
	ds_read_b128 v[152:155], v189 offset:18432
	ds_read_b128 v[156:159], v189 offset:19456
	ds_read_b128 v[160:163], v189 offset:20480
	ds_read_b128 v[174:177], v189 offset:21504
	ds_read_b128 v[178:181], v189 offset:22528
	ds_read_b128 v[182:185], v189 offset:23552
	global_load_lds_dwordx4 v164, s[14:15]
	s_mov_b32 m0, s26
	s_nop 0
	global_load_lds_dwordx4 v166, s[14:15]
	s_barrier
	s_waitcnt lgkmcnt(0)
	v_mfma_f32_16x16x32_bf16 v[60:63], v[108:111], v[144:147], 0
	v_mfma_f32_16x16x32_bf16 v[56:59], v[116:119], v[144:147], 0
	v_mfma_f32_16x16x32_bf16 v[48:51], v[108:111], v[152:155], 0
	v_mfma_f32_16x16x32_bf16 v[40:43], v[116:119], v[152:155], 0
	v_mfma_f32_16x16x32_bf16 v[32:35], v[108:111], v[160:163], 0
	v_mfma_f32_16x16x32_bf16 v[24:27], v[116:119], v[160:163], 0
	v_mfma_f32_16x16x32_bf16 v[16:19], v[108:111], v[178:181], 0
	v_mfma_f32_16x16x32_bf16 v[8:11], v[116:119], v[178:181], 0
	v_mfma_f32_16x16x32_bf16 v[60:63], v[112:115], v[148:151], v[60:63]
	v_mfma_f32_16x16x32_bf16 v[56:59], v[120:123], v[148:151], v[56:59]
	v_mfma_f32_16x16x32_bf16 v[48:51], v[112:115], v[156:159], v[48:51]
	v_mfma_f32_16x16x32_bf16 v[40:43], v[120:123], v[156:159], v[40:43]
	v_mfma_f32_16x16x32_bf16 v[32:35], v[112:115], v[174:177], v[32:35]
	v_mfma_f32_16x16x32_bf16 v[24:27], v[120:123], v[174:177], v[24:27]
	v_mfma_f32_16x16x32_bf16 v[16:19], v[112:115], v[182:185], v[16:19]
	v_mfma_f32_16x16x32_bf16 v[8:11], v[120:123], v[182:185], v[8:11]
	s_barrier
	s_add_u32 s8, s12, 0x160000
	s_addc_u32 s9, s13, 0
	s_add_i32 s42, s43, s19
	s_mov_b32 m0, s42
	s_nop 0
	global_load_lds_dwordx4 v192, s[8:9]
	s_add_i32 m0, s42, 0x2000
	s_nop 0
	global_load_lds_dwordx4 v168, s[8:9]
	s_waitcnt vmcnt(6)
	s_barrier
	v_mfma_f32_16x16x32_bf16 v[52:55], v[196:199], v[144:147], 0
	v_mfma_f32_16x16x32_bf16 v[44:47], v[208:211], v[144:147], 0
	v_mfma_f32_16x16x32_bf16 v[36:39], v[196:199], v[152:155], 0
	v_mfma_f32_16x16x32_bf16 v[28:31], v[208:211], v[152:155], 0
	v_mfma_f32_16x16x32_bf16 v[20:23], v[196:199], v[160:163], 0
	v_mfma_f32_16x16x32_bf16 v[12:15], v[208:211], v[160:163], 0
	v_mfma_f32_16x16x32_bf16 v[4:7], v[196:199], v[178:181], 0
	v_mfma_f32_16x16x32_bf16 v[0:3], v[208:211], v[178:181], 0
	v_mfma_f32_16x16x32_bf16 v[52:55], v[204:207], v[148:151], v[52:55]
	v_mfma_f32_16x16x32_bf16 v[44:47], v[214:217], v[148:151], v[44:47]
	v_mfma_f32_16x16x32_bf16 v[36:39], v[204:207], v[156:159], v[36:39]
	v_mfma_f32_16x16x32_bf16 v[28:31], v[214:217], v[156:159], v[28:31]
	v_mfma_f32_16x16x32_bf16 v[20:23], v[204:207], v[174:177], v[20:23]
	v_mfma_f32_16x16x32_bf16 v[12:15], v[214:217], v[174:177], v[12:15]
	v_mfma_f32_16x16x32_bf16 v[4:7], v[204:207], v[182:185], v[4:7]
	v_mfma_f32_16x16x32_bf16 v[0:3], v[214:217], v[182:185], v[0:3]
	s_add_i32 s42, 0, 0x18000
	s_barrier
	ds_read_b128 v[108:111], v220 offset:32768
	ds_read_b128 v[112:115], v220 offset:33792
	ds_read_b128 v[116:119], v220 offset:34816
	ds_read_b128 v[120:123], v220 offset:35840
	s_add_u32 s8, s14, 0x160000
	s_addc_u32 s9, s15, 0
	s_mov_b32 m0, s27
	ds_read_b128 v[144:147], v189 offset:32768
	ds_read_b128 v[148:151], v189 offset:33792
	ds_read_b128 v[152:155], v189 offset:34816
	ds_read_b128 v[156:159], v189 offset:35840
	ds_read_b128 v[160:163], v189 offset:36864
	ds_read_b128 v[174:177], v189 offset:37888
	ds_read_b128 v[178:181], v189 offset:38912
	ds_read_b128 v[182:185], v189 offset:39936
	global_load_lds_dwordx4 v164, s[8:9]
	s_mov_b32 m0, s28
	s_nop 0
	global_load_lds_dwordx4 v166, s[8:9]
	s_waitcnt lgkmcnt(8)
	s_barrier
	s_waitcnt lgkmcnt(0)
	v_mfma_f32_16x16x32_bf16 v[140:143], v[108:111], v[144:147], v[140:143]
	v_mfma_f32_16x16x32_bf16 v[136:139], v[116:119], v[144:147], v[136:139]
	v_mfma_f32_16x16x32_bf16 v[132:135], v[108:111], v[152:155], v[132:135]
	v_mfma_f32_16x16x32_bf16 v[104:107], v[116:119], v[152:155], v[104:107]
	v_mfma_f32_16x16x32_bf16 v[96:99], v[108:111], v[160:163], v[96:99]
	v_mfma_f32_16x16x32_bf16 v[88:91], v[116:119], v[160:163], v[88:91]
	v_mfma_f32_16x16x32_bf16 v[80:83], v[108:111], v[178:181], v[80:83]
	v_mfma_f32_16x16x32_bf16 v[72:75], v[116:119], v[178:181], v[72:75]
	v_mfma_f32_16x16x32_bf16 v[140:143], v[112:115], v[148:151], v[140:143]
	v_mfma_f32_16x16x32_bf16 v[136:139], v[120:123], v[148:151], v[136:139]
	v_mfma_f32_16x16x32_bf16 v[132:135], v[112:115], v[156:159], v[132:135]
	v_mfma_f32_16x16x32_bf16 v[104:107], v[120:123], v[156:159], v[104:107]
	v_mfma_f32_16x16x32_bf16 v[96:99], v[112:115], v[174:177], v[96:99]
	v_mfma_f32_16x16x32_bf16 v[88:91], v[120:123], v[174:177], v[88:91]
	v_mfma_f32_16x16x32_bf16 v[80:83], v[112:115], v[182:185], v[80:83]
	v_mfma_f32_16x16x32_bf16 v[72:75], v[120:123], v[182:185], v[72:75]
	s_barrier
	s_add_i32 s14, 0, 0x1c000
	s_add_i32 s8, s42, s19
	s_add_i32 m0, s8, 0xffffff80
	ds_read_b128 v[196:199], v220 offset:49152
	ds_read_b128 v[204:207], v220 offset:50176
	ds_read_b128 v[208:211], v220 offset:51200
	ds_read_b128 v[214:217], v220 offset:52224
	global_load_lds_dwordx4 v192, s[12:13] offset:128
	s_add_i32 m0, s8, 0x1f80
	s_nop 0
	global_load_lds_dwordx4 v168, s[12:13] offset:128
	s_barrier
	s_waitcnt lgkmcnt(0)
	v_mfma_f32_16x16x32_bf16 v[128:131], v[196:199], v[144:147], v[128:131]
	v_mfma_f32_16x16x32_bf16 v[124:127], v[208:211], v[144:147], v[124:127]
	v_mfma_f32_16x16x32_bf16 v[100:103], v[196:199], v[152:155], v[100:103]
	v_mfma_f32_16x16x32_bf16 v[92:95], v[208:211], v[152:155], v[92:95]
	v_mfma_f32_16x16x32_bf16 v[84:87], v[196:199], v[160:163], v[84:87]
	v_mfma_f32_16x16x32_bf16 v[76:79], v[208:211], v[160:163], v[76:79]
	v_mfma_f32_16x16x32_bf16 v[68:71], v[196:199], v[178:181], v[68:71]
	v_mfma_f32_16x16x32_bf16 v[64:67], v[208:211], v[178:181], v[64:67]
	v_mfma_f32_16x16x32_bf16 v[128:131], v[204:207], v[148:151], v[128:131]
	v_mfma_f32_16x16x32_bf16 v[124:127], v[214:217], v[148:151], v[124:127]
	v_mfma_f32_16x16x32_bf16 v[100:103], v[204:207], v[156:159], v[100:103]
	v_mfma_f32_16x16x32_bf16 v[92:95], v[214:217], v[156:159], v[92:95]
	v_mfma_f32_16x16x32_bf16 v[84:87], v[204:207], v[174:177], v[84:87]
	v_mfma_f32_16x16x32_bf16 v[76:79], v[214:217], v[174:177], v[76:79]
	v_mfma_f32_16x16x32_bf16 v[68:71], v[204:207], v[182:185], v[68:71]
	v_mfma_f32_16x16x32_bf16 v[64:67], v[214:217], v[182:185], v[64:67]
	s_mov_b32 m0, s31
	s_barrier
	ds_read_b128 v[144:147], v189 offset:49152
	ds_read_b128 v[148:151], v189 offset:50176
	ds_read_b128 v[152:155], v189 offset:51200
	ds_read_b128 v[156:159], v189 offset:52224
	ds_read_b128 v[160:163], v189 offset:53248
	ds_read_b128 v[174:177], v189 offset:54272
	ds_read_b128 v[178:181], v189 offset:55296
	ds_read_b128 v[182:185], v189 offset:56320
	global_load_lds_dwordx4 v164, s[44:45]
	s_mov_b32 m0, s33
	s_nop 0
	global_load_lds_dwordx4 v166, s[44:45]
	s_barrier
	s_waitcnt lgkmcnt(0)
	v_mfma_f32_16x16x32_bf16 v[60:63], v[108:111], v[144:147], v[60:63]
	v_mfma_f32_16x16x32_bf16 v[56:59], v[116:119], v[144:147], v[56:59]
	v_mfma_f32_16x16x32_bf16 v[48:51], v[108:111], v[152:155], v[48:51]
	v_mfma_f32_16x16x32_bf16 v[40:43], v[116:119], v[152:155], v[40:43]
	v_mfma_f32_16x16x32_bf16 v[32:35], v[108:111], v[160:163], v[32:35]
	v_mfma_f32_16x16x32_bf16 v[24:27], v[116:119], v[160:163], v[24:27]
	v_mfma_f32_16x16x32_bf16 v[16:19], v[108:111], v[178:181], v[16:19]
	v_mfma_f32_16x16x32_bf16 v[8:11], v[116:119], v[178:181], v[8:11]
	v_mfma_f32_16x16x32_bf16 v[60:63], v[112:115], v[148:151], v[60:63]
	v_mfma_f32_16x16x32_bf16 v[56:59], v[120:123], v[148:151], v[56:59]
	v_mfma_f32_16x16x32_bf16 v[48:51], v[112:115], v[156:159], v[48:51]
	v_mfma_f32_16x16x32_bf16 v[40:43], v[120:123], v[156:159], v[40:43]
	v_mfma_f32_16x16x32_bf16 v[32:35], v[112:115], v[174:177], v[32:35]
	v_mfma_f32_16x16x32_bf16 v[24:27], v[120:123], v[174:177], v[24:27]
	v_mfma_f32_16x16x32_bf16 v[16:19], v[112:115], v[182:185], v[16:19]
	v_mfma_f32_16x16x32_bf16 v[8:11], v[120:123], v[182:185], v[8:11]
	s_barrier
	s_add_u32 s8, s12, 0x160080
	s_addc_u32 s9, s13, 0
	s_add_i32 s12, s14, s19
	s_mov_b32 m0, s12
	s_nop 0
	global_load_lds_dwordx4 v192, s[8:9]
	s_add_i32 m0, s12, 0x2000
	s_nop 0
	global_load_lds_dwordx4 v168, s[8:9]
	s_waitcnt vmcnt(6)
	s_barrier
	v_mfma_f32_16x16x32_bf16 v[52:55], v[196:199], v[144:147], v[52:55]
	v_mfma_f32_16x16x32_bf16 v[44:47], v[208:211], v[144:147], v[44:47]
	v_mfma_f32_16x16x32_bf16 v[36:39], v[196:199], v[152:155], v[36:39]
	v_mfma_f32_16x16x32_bf16 v[28:31], v[208:211], v[152:155], v[28:31]
	v_mfma_f32_16x16x32_bf16 v[20:23], v[196:199], v[160:163], v[20:23]
	v_mfma_f32_16x16x32_bf16 v[12:15], v[208:211], v[160:163], v[12:15]
	v_mfma_f32_16x16x32_bf16 v[4:7], v[196:199], v[178:181], v[4:7]
	v_mfma_f32_16x16x32_bf16 v[0:3], v[208:211], v[178:181], v[0:3]
	v_mfma_f32_16x16x32_bf16 v[52:55], v[204:207], v[148:151], v[52:55]
	v_mfma_f32_16x16x32_bf16 v[44:47], v[214:217], v[148:151], v[44:47]
	v_mfma_f32_16x16x32_bf16 v[36:39], v[204:207], v[156:159], v[36:39]
	v_mfma_f32_16x16x32_bf16 v[28:31], v[214:217], v[156:159], v[28:31]
	v_mfma_f32_16x16x32_bf16 v[20:23], v[204:207], v[174:177], v[20:23]
	v_mfma_f32_16x16x32_bf16 v[12:15], v[214:217], v[174:177], v[12:15]
	v_mfma_f32_16x16x32_bf16 v[4:7], v[204:207], v[182:185], v[4:7]
	v_mfma_f32_16x16x32_bf16 v[0:3], v[214:217], v[182:185], v[0:3]
	s_add_i32 s41, s41, 2
	s_add_u32 s39, s39, 0x100
	s_addc_u32 s40, s40, 0
	s_cmpk_gt_u32 s41, 0x55
	s_mov_b64 s[8:9], s[10:11]
	s_barrier

.LBB0_293:
	v_mov_b64_e32 v[0:1], 0x400
	s_ashr_i32 s7, s6, 31
	v_cmp_lt_i64_e32 vcc, s[8:9], v[0:1]
	s_lshl_b64 s[8:9], s[6:7], 20
	s_add_u32 s8, s20, s8
	s_addc_u32 s9, s21, s9
	s_and_b64 s[10:11], vcc, exec
	s_cselect_b32 s7, s9, s15
	s_cselect_b32 s38, s8, s14
	s_ashr_i32 s5, s4, 31
	s_lshl_b64 s[10:11], s[4:5], 20
	s_add_u32 s10, s22, s10
	s_addc_u32 s11, s23, s11
	s_and_b64 s[18:19], vcc, exec
	s_cselect_b32 s5, s11, s17
	s_cselect_b32 s39, s10, s16
	s_add_u32 s14, s14, 0x80080
	s_addc_u32 s15, s15, 0
	s_add_u32 s40, s16, 0x100
	s_addc_u32 s41, s17, 0
	s_mov_b32 s42, -2
	s_mov_b64 s[48:49], 0x80
	v_add_u32_e32 v220, 0x10000, v159
	s_add_u32 s16, s14, 0xfff80080
	s_addc_u32 s17, s15, -1
	s_add_i32 s43, 0, 0x10000
	ds_read_b128 v[64:67], v220 offset:0
	ds_read_b128 v[68:71], v220 offset:1024
	ds_read_b128 v[72:75], v220 offset:2048
	ds_read_b128 v[76:79], v220 offset:3072
	s_cmp_eq_u32 s42, 28
	s_cselect_b32 s19, s7, s17
	s_cselect_b32 s18, s38, s16
	s_cselect_b32 s17, s5, s41
	s_cselect_b32 s16, s39, s40
	s_add_i32 m0, s13, 0xc000
	ds_read_b128 v[154:157], v161
	ds_read_b128 v[162:165], v161 offset:1024
	ds_read_b128 v[166:169], v161 offset:2048
	ds_read_b128 v[170:173], v161 offset:3072
	ds_read_b128 v[174:177], v161 offset:4096
	ds_read_b128 v[178:181], v161 offset:5120
	ds_read_b128 v[182:185], v161 offset:6144
	ds_read_b128 v[186:189], v161 offset:7168
	global_load_lds_dwordx4 v150, s[14:15]
	s_add_i32 m0, s13, 0xe000
	s_nop 0
	global_load_lds_dwordx4 v152, s[14:15]
	s_waitcnt lgkmcnt(8)
	s_barrier
	s_waitcnt lgkmcnt(0)
	v_mfma_f32_16x16x32_bf16 v[140:143], v[64:67], v[154:157], 0
	v_mfma_f32_16x16x32_bf16 v[136:139], v[72:75], v[154:157], 0
	v_mfma_f32_16x16x32_bf16 v[132:135], v[64:67], v[166:169], 0
	v_mfma_f32_16x16x32_bf16 v[128:131], v[72:75], v[166:169], 0
	v_mfma_f32_16x16x32_bf16 v[108:111], v[64:67], v[174:177], 0
	v_mfma_f32_16x16x32_bf16 v[104:107], v[72:75], v[174:177], 0
	v_mfma_f32_16x16x32_bf16 v[100:103], v[64:67], v[182:185], 0
	v_mfma_f32_16x16x32_bf16 v[96:99], v[72:75], v[182:185], 0
	v_mfma_f32_16x16x32_bf16 v[140:143], v[68:71], v[162:165], v[140:143]
	v_mfma_f32_16x16x32_bf16 v[136:139], v[76:79], v[162:165], v[136:139]
	v_mfma_f32_16x16x32_bf16 v[132:135], v[68:71], v[170:173], v[132:135]
	v_mfma_f32_16x16x32_bf16 v[128:131], v[76:79], v[170:173], v[128:131]
	v_mfma_f32_16x16x32_bf16 v[108:111], v[68:71], v[178:181], v[108:111]
	v_mfma_f32_16x16x32_bf16 v[104:107], v[76:79], v[178:181], v[104:107]
	v_mfma_f32_16x16x32_bf16 v[100:103], v[68:71], v[186:189], v[100:103]
	v_mfma_f32_16x16x32_bf16 v[96:99], v[76:79], v[186:189], v[96:99]
	s_barrier
	s_add_i32 s46, 0, 0x14000
	s_add_i32 s43, s43, s27
	ds_read_b128 v[196:199], v220 offset:16384
	ds_read_b128 v[204:207], v220 offset:17408
	ds_read_b128 v[208:211], v220 offset:18432
	ds_read_b128 v[214:217], v220 offset:19456
	s_mov_b32 m0, s43
	s_nop 0
	global_load_lds_dwordx4 v192, s[16:17]
	s_add_i32 m0, s43, 0x2000
	s_nop 0
	global_load_lds_dwordx4 v148, s[16:17]
	s_barrier
	s_waitcnt lgkmcnt(0)
	v_mfma_f32_16x16x32_bf16 v[124:127], v[196:199], v[154:157], 0
	v_mfma_f32_16x16x32_bf16 v[120:123], v[208:211], v[154:157], 0
	v_mfma_f32_16x16x32_bf16 v[116:119], v[196:199], v[166:169], 0
	v_mfma_f32_16x16x32_bf16 v[112:115], v[208:211], v[166:169], 0
	v_mfma_f32_16x16x32_bf16 v[92:95], v[196:199], v[174:177], 0
	v_mfma_f32_16x16x32_bf16 v[88:91], v[208:211], v[174:177], 0
	v_mfma_f32_16x16x32_bf16 v[84:87], v[196:199], v[182:185], 0
	v_mfma_f32_16x16x32_bf16 v[80:83], v[208:211], v[182:185], 0
	v_mfma_f32_16x16x32_bf16 v[124:127], v[204:207], v[162:165], v[124:127]
	v_mfma_f32_16x16x32_bf16 v[120:123], v[214:217], v[162:165], v[120:123]
	v_mfma_f32_16x16x32_bf16 v[116:119], v[204:207], v[170:173], v[116:119]
	v_mfma_f32_16x16x32_bf16 v[112:115], v[214:217], v[170:173], v[112:115]
	v_mfma_f32_16x16x32_bf16 v[92:95], v[204:207], v[178:181], v[92:95]
	v_mfma_f32_16x16x32_bf16 v[88:91], v[214:217], v[178:181], v[88:91]
	v_mfma_f32_16x16x32_bf16 v[84:87], v[204:207], v[186:189], v[84:87]
	v_mfma_f32_16x16x32_bf16 v[80:83], v[214:217], v[186:189], v[80:83]
	s_mov_b32 m0, s13
	s_add_u32 s48, s18, 0x80
	s_addc_u32 s49, s19, 0
	s_barrier
	ds_read_b128 v[154:157], v161 offset:16384
	ds_read_b128 v[162:165], v161 offset:17408
	ds_read_b128 v[166:169], v161 offset:18432
	ds_read_b128 v[170:173], v161 offset:19456
	ds_read_b128 v[174:177], v161 offset:20480
	ds_read_b128 v[178:181], v161 offset:21504
	ds_read_b128 v[182:185], v161 offset:22528
	ds_read_b128 v[186:189], v161 offset:23552
	global_load_lds_dwordx4 v144, s[18:19]
	s_mov_b32 m0, s28
	s_nop 0
	global_load_lds_dwordx4 v146, s[18:19]
	s_barrier
	s_waitcnt lgkmcnt(0)
	v_mfma_f32_16x16x32_bf16 v[60:63], v[64:67], v[154:157], 0
	v_mfma_f32_16x16x32_bf16 v[56:59], v[72:75], v[154:157], 0
	v_mfma_f32_16x16x32_bf16 v[52:55], v[64:67], v[166:169], 0
	v_mfma_f32_16x16x32_bf16 v[48:51], v[72:75], v[166:169], 0
	v_mfma_f32_16x16x32_bf16 v[28:31], v[64:67], v[174:177], 0
	v_mfma_f32_16x16x32_bf16 v[24:27], v[72:75], v[174:177], 0
	v_mfma_f32_16x16x32_bf16 v[20:23], v[64:67], v[182:185], 0
	v_mfma_f32_16x16x32_bf16 v[16:19], v[72:75], v[182:185], 0
	v_mfma_f32_16x16x32_bf16 v[60:63], v[68:71], v[162:165], v[60:63]
	v_mfma_f32_16x16x32_bf16 v[56:59], v[76:79], v[162:165], v[56:59]
	v_mfma_f32_16x16x32_bf16 v[52:55], v[68:71], v[170:173], v[52:55]
	v_mfma_f32_16x16x32_bf16 v[48:51], v[76:79], v[170:173], v[48:51]
	v_mfma_f32_16x16x32_bf16 v[28:31], v[68:71], v[178:181], v[28:31]
	v_mfma_f32_16x16x32_bf16 v[24:27], v[76:79], v[178:181], v[24:27]
	v_mfma_f32_16x16x32_bf16 v[20:23], v[68:71], v[186:189], v[20:23]
	v_mfma_f32_16x16x32_bf16 v[16:19], v[76:79], v[186:189], v[16:19]
	s_barrier
	s_add_u32 s44, s16, 0x80000
	s_addc_u32 s45, s17, 0
	s_add_i32 s43, s46, s27
	s_mov_b32 m0, s43
	s_nop 0
	global_load_lds_dwordx4 v192, s[44:45]
	s_add_i32 m0, s43, 0x2000
	s_nop 0
	global_load_lds_dwordx4 v148, s[44:45]
	s_waitcnt vmcnt(6)
	s_barrier
	v_mfma_f32_16x16x32_bf16 v[44:47], v[196:199], v[154:157], 0
	v_mfma_f32_16x16x32_bf16 v[40:43], v[208:211], v[154:157], 0
	v_mfma_f32_16x16x32_bf16 v[36:39], v[196:199], v[166:169], 0
	v_mfma_f32_16x16x32_bf16 v[32:35], v[208:211], v[166:169], 0
	v_mfma_f32_16x16x32_bf16 v[12:15], v[196:199], v[174:177], 0
	v_mfma_f32_16x16x32_bf16 v[8:11], v[208:211], v[174:177], 0
	v_mfma_f32_16x16x32_bf16 v[4:7], v[196:199], v[182:185], 0
	v_mfma_f32_16x16x32_bf16 v[0:3], v[208:211], v[182:185], 0
	v_mfma_f32_16x16x32_bf16 v[44:47], v[204:207], v[162:165], v[44:47]
	v_mfma_f32_16x16x32_bf16 v[40:43], v[214:217], v[162:165], v[40:43]
	v_mfma_f32_16x16x32_bf16 v[36:39], v[204:207], v[170:173], v[36:39]
	v_mfma_f32_16x16x32_bf16 v[32:35], v[214:217], v[170:173], v[32:35]
	v_mfma_f32_16x16x32_bf16 v[12:15], v[204:207], v[178:181], v[12:15]
	v_mfma_f32_16x16x32_bf16 v[8:11], v[214:217], v[178:181], v[8:11]
	v_mfma_f32_16x16x32_bf16 v[4:7], v[204:207], v[186:189], v[4:7]
	v_mfma_f32_16x16x32_bf16 v[0:3], v[214:217], v[186:189], v[0:3]
	s_add_i32 s43, 0, 0x18000
	s_barrier
	ds_read_b128 v[64:67], v220 offset:32768
	ds_read_b128 v[68:71], v220 offset:33792
	ds_read_b128 v[72:75], v220 offset:34816
	ds_read_b128 v[76:79], v220 offset:35840
	s_add_u32 s18, s18, 0x80000
	s_addc_u32 s19, s19, 0
	s_mov_b32 m0, s29
	ds_read_b128 v[154:157], v161 offset:32768
	ds_read_b128 v[162:165], v161 offset:33792
	ds_read_b128 v[166:169], v161 offset:34816
	ds_read_b128 v[170:173], v161 offset:35840
	ds_read_b128 v[174:177], v161 offset:36864
	ds_read_b128 v[178:181], v161 offset:37888
	ds_read_b128 v[182:185], v161 offset:38912
	ds_read_b128 v[186:189], v161 offset:39936
	global_load_lds_dwordx4 v144, s[18:19]
	s_mov_b32 m0, s30
	s_nop 0
	global_load_lds_dwordx4 v146, s[18:19]
	s_waitcnt lgkmcnt(8)
	s_barrier
	s_waitcnt lgkmcnt(0)
	v_mfma_f32_16x16x32_bf16 v[140:143], v[64:67], v[154:157], v[140:143]
	v_mfma_f32_16x16x32_bf16 v[136:139], v[72:75], v[154:157], v[136:139]
	v_mfma_f32_16x16x32_bf16 v[132:135], v[64:67], v[166:169], v[132:135]
	v_mfma_f32_16x16x32_bf16 v[128:131], v[72:75], v[166:169], v[128:131]
	v_mfma_f32_16x16x32_bf16 v[108:111], v[64:67], v[174:177], v[108:111]
	v_mfma_f32_16x16x32_bf16 v[104:107], v[72:75], v[174:177], v[104:107]
	v_mfma_f32_16x16x32_bf16 v[100:103], v[64:67], v[182:185], v[100:103]
	v_mfma_f32_16x16x32_bf16 v[96:99], v[72:75], v[182:185], v[96:99]
	v_mfma_f32_16x16x32_bf16 v[140:143], v[68:71], v[162:165], v[140:143]
	v_mfma_f32_16x16x32_bf16 v[136:139], v[76:79], v[162:165], v[136:139]
	v_mfma_f32_16x16x32_bf16 v[132:135], v[68:71], v[170:173], v[132:135]
	v_mfma_f32_16x16x32_bf16 v[128:131], v[76:79], v[170:173], v[128:131]
	v_mfma_f32_16x16x32_bf16 v[108:111], v[68:71], v[178:181], v[108:111]
	v_mfma_f32_16x16x32_bf16 v[104:107], v[76:79], v[178:181], v[104:107]
	v_mfma_f32_16x16x32_bf16 v[100:103], v[68:71], v[186:189], v[100:103]
	v_mfma_f32_16x16x32_bf16 v[96:99], v[76:79], v[186:189], v[96:99]
	s_barrier
	s_add_i32 s18, 0, 0x1c000
	s_add_i32 s19, s43, s27
	s_add_i32 m0, s19, 0xffffff80
	ds_read_b128 v[196:199], v220 offset:49152
	ds_read_b128 v[204:207], v220 offset:50176
	ds_read_b128 v[208:211], v220 offset:51200
	ds_read_b128 v[214:217], v220 offset:52224
	global_load_lds_dwordx4 v192, s[16:17] offset:128
	s_add_i32 m0, s19, 0x1f80
	s_nop 0
	global_load_lds_dwordx4 v148, s[16:17] offset:128
	s_barrier
	s_waitcnt lgkmcnt(0)
	v_mfma_f32_16x16x32_bf16 v[124:127], v[196:199], v[154:157], v[124:127]
	v_mfma_f32_16x16x32_bf16 v[120:123], v[208:211], v[154:157], v[120:123]
	v_mfma_f32_16x16x32_bf16 v[116:119], v[196:199], v[166:169], v[116:119]
	v_mfma_f32_16x16x32_bf16 v[112:115], v[208:211], v[166:169], v[112:115]
	v_mfma_f32_16x16x32_bf16 v[92:95], v[196:199], v[174:177], v[92:95]
	v_mfma_f32_16x16x32_bf16 v[88:91], v[208:211], v[174:177], v[88:91]
	v_mfma_f32_16x16x32_bf16 v[84:87], v[196:199], v[182:185], v[84:87]
	v_mfma_f32_16x16x32_bf16 v[80:83], v[208:211], v[182:185], v[80:83]
	v_mfma_f32_16x16x32_bf16 v[124:127], v[204:207], v[162:165], v[124:127]
	v_mfma_f32_16x16x32_bf16 v[120:123], v[214:217], v[162:165], v[120:123]
	v_mfma_f32_16x16x32_bf16 v[116:119], v[204:207], v[170:173], v[116:119]
	v_mfma_f32_16x16x32_bf16 v[112:115], v[214:217], v[170:173], v[112:115]
	v_mfma_f32_16x16x32_bf16 v[92:95], v[204:207], v[178:181], v[92:95]
	v_mfma_f32_16x16x32_bf16 v[88:91], v[214:217], v[178:181], v[88:91]
	v_mfma_f32_16x16x32_bf16 v[84:87], v[204:207], v[186:189], v[84:87]
	v_mfma_f32_16x16x32_bf16 v[80:83], v[214:217], v[186:189], v[80:83]
	s_mov_b32 m0, s34
	s_barrier
	ds_read_b128 v[154:157], v161 offset:49152
	ds_read_b128 v[162:165], v161 offset:50176
	ds_read_b128 v[166:169], v161 offset:51200
	ds_read_b128 v[170:173], v161 offset:52224
	ds_read_b128 v[174:177], v161 offset:53248
	ds_read_b128 v[178:181], v161 offset:54272
	ds_read_b128 v[182:185], v161 offset:55296
	ds_read_b128 v[186:189], v161 offset:56320
	global_load_lds_dwordx4 v144, s[48:49]
	s_mov_b32 m0, s35
	s_nop 0
	global_load_lds_dwordx4 v146, s[48:49]
	s_barrier
	s_waitcnt lgkmcnt(0)
	v_mfma_f32_16x16x32_bf16 v[60:63], v[64:67], v[154:157], v[60:63]
	v_mfma_f32_16x16x32_bf16 v[56:59], v[72:75], v[154:157], v[56:59]
	v_mfma_f32_16x16x32_bf16 v[52:55], v[64:67], v[166:169], v[52:55]
	v_mfma_f32_16x16x32_bf16 v[48:51], v[72:75], v[166:169], v[48:51]
	v_mfma_f32_16x16x32_bf16 v[28:31], v[64:67], v[174:177], v[28:31]
	v_mfma_f32_16x16x32_bf16 v[24:27], v[72:75], v[174:177], v[24:27]
	v_mfma_f32_16x16x32_bf16 v[20:23], v[64:67], v[182:185], v[20:23]
	v_mfma_f32_16x16x32_bf16 v[16:19], v[72:75], v[182:185], v[16:19]
	v_mfma_f32_16x16x32_bf16 v[60:63], v[68:71], v[162:165], v[60:63]
	v_mfma_f32_16x16x32_bf16 v[56:59], v[76:79], v[162:165], v[56:59]
	v_mfma_f32_16x16x32_bf16 v[52:55], v[68:71], v[170:173], v[52:55]
	v_mfma_f32_16x16x32_bf16 v[48:51], v[76:79], v[170:173], v[48:51]
	v_mfma_f32_16x16x32_bf16 v[28:31], v[68:71], v[178:181], v[28:31]
	v_mfma_f32_16x16x32_bf16 v[24:27], v[76:79], v[178:181], v[24:27]
	v_mfma_f32_16x16x32_bf16 v[20:23], v[68:71], v[186:189], v[20:23]
	v_mfma_f32_16x16x32_bf16 v[16:19], v[76:79], v[186:189], v[16:19]
	s_barrier
	s_add_u32 s16, s16, 0x80080
	s_addc_u32 s17, s17, 0
	s_add_i32 s18, s18, s27
	s_mov_b32 m0, s18
	s_nop 0
	global_load_lds_dwordx4 v192, s[16:17]
	s_add_i32 m0, s18, 0x2000
	s_nop 0
	global_load_lds_dwordx4 v148, s[16:17]
	s_waitcnt vmcnt(6)
	s_barrier
	v_mfma_f32_16x16x32_bf16 v[44:47], v[196:199], v[154:157], v[44:47]
	v_mfma_f32_16x16x32_bf16 v[40:43], v[208:211], v[154:157], v[40:43]
	v_mfma_f32_16x16x32_bf16 v[36:39], v[196:199], v[166:169], v[36:39]
	v_mfma_f32_16x16x32_bf16 v[32:35], v[208:211], v[166:169], v[32:35]
	v_mfma_f32_16x16x32_bf16 v[12:15], v[196:199], v[174:177], v[12:15]
	v_mfma_f32_16x16x32_bf16 v[8:11], v[208:211], v[174:177], v[8:11]
	v_mfma_f32_16x16x32_bf16 v[4:7], v[196:199], v[182:185], v[4:7]
	v_mfma_f32_16x16x32_bf16 v[0:3], v[208:211], v[182:185], v[0:3]
	v_mfma_f32_16x16x32_bf16 v[44:47], v[204:207], v[162:165], v[44:47]
	v_mfma_f32_16x16x32_bf16 v[40:43], v[214:217], v[162:165], v[40:43]
	v_mfma_f32_16x16x32_bf16 v[36:39], v[204:207], v[170:173], v[36:39]
	v_mfma_f32_16x16x32_bf16 v[32:35], v[214:217], v[170:173], v[32:35]
	v_mfma_f32_16x16x32_bf16 v[12:15], v[204:207], v[178:181], v[12:15]
	v_mfma_f32_16x16x32_bf16 v[8:11], v[214:217], v[178:181], v[8:11]
	v_mfma_f32_16x16x32_bf16 v[4:7], v[204:207], v[186:189], v[4:7]
	v_mfma_f32_16x16x32_bf16 v[0:3], v[214:217], v[186:189], v[0:3]
	s_add_i32 s42, s42, 2
	s_add_u32 s14, s14, 0x100
	s_addc_u32 s15, s15, 0
	s_add_u32 s40, s40, 0x100
	s_addc_u32 s41, s41, 0
	s_cmp_gt_u32 s42, 29
	s_barrier

.LBB0_414:
	s_ashr_i32 s9, s8, 31
	v_cmp_lt_i64_e32 vcc, s[10:11], v[202:203]
	s_lshl_b64 s[10:11], s[8:9], 20
	s_add_u32 s10, s24, s10
	s_addc_u32 s11, s25, s11
	s_and_b64 s[12:13], vcc, exec
	s_cselect_b32 s9, s11, s17
	s_cselect_b32 s38, s10, s16
	s_ashr_i32 s7, s6, 31
	s_lshl_b64 s[12:13], s[6:7], 20
	s_add_u32 s12, s26, s12
	s_addc_u32 s13, s27, s13
	s_and_b64 s[20:21], vcc, exec
	s_cselect_b32 s7, s13, s19
	s_cselect_b32 s39, s12, s18
	s_add_u32 s16, s16, 0x80080
	s_addc_u32 s17, s17, 0
	s_add_u32 s40, s18, 0x100
	s_addc_u32 s41, s19, 0
	s_mov_b32 s42, -2
	s_mov_b64 s[48:49], 0x80
	v_add_u32_e32 v196, 0x10000, v143
	s_add_u32 s18, s16, 0xfff80080
	s_addc_u32 s19, s17, -1
	s_add_i32 s43, 0, 0x10000
	ds_read_b128 v[146:149], v196 offset:0
	ds_read_b128 v[150:153], v196 offset:1024
	ds_read_b128 v[154:157], v196 offset:2048
	ds_read_b128 v[158:161], v196 offset:3072
	s_cmp_eq_u32 s42, 28
	s_cselect_b32 s21, s9, s19
	s_cselect_b32 s20, s38, s18
	s_cselect_b32 s19, s7, s41
	s_cselect_b32 s18, s39, s40
	s_add_i32 m0, s30, 0xc000
	ds_read_b128 v[162:165], v145
	ds_read_b128 v[166:169], v145 offset:1024
	ds_read_b128 v[170:173], v145 offset:2048
	ds_read_b128 v[174:177], v145 offset:3072
	ds_read_b128 v[178:181], v145 offset:4096
	ds_read_b128 v[182:185], v145 offset:5120
	ds_read_b128 v[186:189], v145 offset:6144
	ds_read_b128 v[204:207], v145 offset:7168
	global_load_lds_dwordx4 v136, s[16:17]
	s_add_i32 m0, s30, 0xe000
	s_nop 0
	global_load_lds_dwordx4 v138, s[16:17]
	s_waitcnt lgkmcnt(8)
	s_barrier
	s_waitcnt lgkmcnt(0)
	v_mfma_f32_16x16x32_bf16 v[124:127], v[146:149], v[162:165], 0
	v_mfma_f32_16x16x32_bf16 v[120:123], v[154:157], v[162:165], 0
	v_mfma_f32_16x16x32_bf16 v[116:119], v[146:149], v[170:173], 0
	v_mfma_f32_16x16x32_bf16 v[108:111], v[154:157], v[170:173], 0
	v_mfma_f32_16x16x32_bf16 v[100:103], v[146:149], v[178:181], 0
	v_mfma_f32_16x16x32_bf16 v[92:95], v[154:157], v[178:181], 0
	v_mfma_f32_16x16x32_bf16 v[84:87], v[146:149], v[186:189], 0
	v_mfma_f32_16x16x32_bf16 v[76:79], v[154:157], v[186:189], 0
	v_mfma_f32_16x16x32_bf16 v[124:127], v[150:153], v[166:169], v[124:127]
	v_mfma_f32_16x16x32_bf16 v[120:123], v[158:161], v[166:169], v[120:123]
	v_mfma_f32_16x16x32_bf16 v[116:119], v[150:153], v[174:177], v[116:119]
	v_mfma_f32_16x16x32_bf16 v[108:111], v[158:161], v[174:177], v[108:111]
	v_mfma_f32_16x16x32_bf16 v[100:103], v[150:153], v[182:185], v[100:103]
	v_mfma_f32_16x16x32_bf16 v[92:95], v[158:161], v[182:185], v[92:95]
	v_mfma_f32_16x16x32_bf16 v[84:87], v[150:153], v[204:207], v[84:87]
	v_mfma_f32_16x16x32_bf16 v[76:79], v[158:161], v[204:207], v[76:79]
	s_barrier
	s_add_i32 s46, 0, 0x14000
	s_add_i32 s43, s43, s28
	ds_read_b128 v[208:211], v196 offset:16384
	ds_read_b128 v[214:217], v196 offset:17408
	ds_read_b128 v[218:221], v196 offset:18432
	ds_read_b128 v[222:225], v196 offset:19456
	s_mov_b32 m0, s43
	s_nop 0
	global_load_lds_dwordx4 v192, s[18:19]
	s_add_i32 m0, s43, 0x2000
	s_nop 0
	global_load_lds_dwordx4 v128, s[18:19]
	s_barrier
	s_waitcnt lgkmcnt(0)
	v_mfma_f32_16x16x32_bf16 v[112:115], v[208:211], v[162:165], 0
	v_mfma_f32_16x16x32_bf16 v[104:107], v[218:221], v[162:165], 0
	v_mfma_f32_16x16x32_bf16 v[96:99], v[208:211], v[170:173], 0
	v_mfma_f32_16x16x32_bf16 v[88:91], v[218:221], v[170:173], 0
	v_mfma_f32_16x16x32_bf16 v[80:83], v[208:211], v[178:181], 0
	v_mfma_f32_16x16x32_bf16 v[72:75], v[218:221], v[178:181], 0
	v_mfma_f32_16x16x32_bf16 v[68:71], v[208:211], v[186:189], 0
	v_mfma_f32_16x16x32_bf16 v[64:67], v[218:221], v[186:189], 0
	v_mfma_f32_16x16x32_bf16 v[112:115], v[214:217], v[166:169], v[112:115]
	v_mfma_f32_16x16x32_bf16 v[104:107], v[222:225], v[166:169], v[104:107]
	v_mfma_f32_16x16x32_bf16 v[96:99], v[214:217], v[174:177], v[96:99]
	v_mfma_f32_16x16x32_bf16 v[88:91], v[222:225], v[174:177], v[88:91]
	v_mfma_f32_16x16x32_bf16 v[80:83], v[214:217], v[182:185], v[80:83]
	v_mfma_f32_16x16x32_bf16 v[72:75], v[222:225], v[182:185], v[72:75]
	v_mfma_f32_16x16x32_bf16 v[68:71], v[214:217], v[204:207], v[68:71]
	v_mfma_f32_16x16x32_bf16 v[64:67], v[222:225], v[204:207], v[64:67]
	s_mov_b32 m0, s30
	s_add_u32 s48, s20, 0x80
	s_addc_u32 s49, s21, 0
	s_barrier
	ds_read_b128 v[162:165], v145 offset:16384
	ds_read_b128 v[166:169], v145 offset:17408
	ds_read_b128 v[170:173], v145 offset:18432
	ds_read_b128 v[174:177], v145 offset:19456
	ds_read_b128 v[178:181], v145 offset:20480
	ds_read_b128 v[182:185], v145 offset:21504
	ds_read_b128 v[186:189], v145 offset:22528
	ds_read_b128 v[204:207], v145 offset:23552
	global_load_lds_dwordx4 v132, s[20:21]
	s_mov_b32 m0, s31
	s_nop 0
	global_load_lds_dwordx4 v130, s[20:21]
	s_barrier
	s_waitcnt lgkmcnt(0)
	v_mfma_f32_16x16x32_bf16 v[60:63], v[146:149], v[162:165], 0
	v_mfma_f32_16x16x32_bf16 v[56:59], v[154:157], v[162:165], 0
	v_mfma_f32_16x16x32_bf16 v[52:55], v[146:149], v[170:173], 0
	v_mfma_f32_16x16x32_bf16 v[44:47], v[154:157], v[170:173], 0
	v_mfma_f32_16x16x32_bf16 v[36:39], v[146:149], v[178:181], 0
	v_mfma_f32_16x16x32_bf16 v[28:31], v[154:157], v[178:181], 0
	v_mfma_f32_16x16x32_bf16 v[20:23], v[146:149], v[186:189], 0
	v_mfma_f32_16x16x32_bf16 v[12:15], v[154:157], v[186:189], 0
	v_mfma_f32_16x16x32_bf16 v[60:63], v[150:153], v[166:169], v[60:63]
	v_mfma_f32_16x16x32_bf16 v[56:59], v[158:161], v[166:169], v[56:59]
	v_mfma_f32_16x16x32_bf16 v[52:55], v[150:153], v[174:177], v[52:55]
	v_mfma_f32_16x16x32_bf16 v[44:47], v[158:161], v[174:177], v[44:47]
	v_mfma_f32_16x16x32_bf16 v[36:39], v[150:153], v[182:185], v[36:39]
	v_mfma_f32_16x16x32_bf16 v[28:31], v[158:161], v[182:185], v[28:31]
	v_mfma_f32_16x16x32_bf16 v[20:23], v[150:153], v[204:207], v[20:23]
	v_mfma_f32_16x16x32_bf16 v[12:15], v[158:161], v[204:207], v[12:15]
	s_barrier
	s_add_u32 s44, s18, 0x80000
	s_addc_u32 s45, s19, 0
	s_add_i32 s43, s46, s28
	s_mov_b32 m0, s43
	s_nop 0
	global_load_lds_dwordx4 v192, s[44:45]
	s_add_i32 m0, s43, 0x2000
	s_nop 0
	global_load_lds_dwordx4 v128, s[44:45]
	s_waitcnt vmcnt(6)
	s_barrier
	v_mfma_f32_16x16x32_bf16 v[48:51], v[208:211], v[162:165], 0
	v_mfma_f32_16x16x32_bf16 v[40:43], v[218:221], v[162:165], 0
	v_mfma_f32_16x16x32_bf16 v[32:35], v[208:211], v[170:173], 0
	v_mfma_f32_16x16x32_bf16 v[24:27], v[218:221], v[170:173], 0
	v_mfma_f32_16x16x32_bf16 v[16:19], v[208:211], v[178:181], 0
	v_mfma_f32_16x16x32_bf16 v[8:11], v[218:221], v[178:181], 0
	v_mfma_f32_16x16x32_bf16 v[4:7], v[208:211], v[186:189], 0
	v_mfma_f32_16x16x32_bf16 v[0:3], v[218:221], v[186:189], 0
	v_mfma_f32_16x16x32_bf16 v[48:51], v[214:217], v[166:169], v[48:51]
	v_mfma_f32_16x16x32_bf16 v[40:43], v[222:225], v[166:169], v[40:43]
	v_mfma_f32_16x16x32_bf16 v[32:35], v[214:217], v[174:177], v[32:35]
	v_mfma_f32_16x16x32_bf16 v[24:27], v[222:225], v[174:177], v[24:27]
	v_mfma_f32_16x16x32_bf16 v[16:19], v[214:217], v[182:185], v[16:19]
	v_mfma_f32_16x16x32_bf16 v[8:11], v[222:225], v[182:185], v[8:11]
	v_mfma_f32_16x16x32_bf16 v[4:7], v[214:217], v[204:207], v[4:7]
	v_mfma_f32_16x16x32_bf16 v[0:3], v[222:225], v[204:207], v[0:3]
	s_add_i32 s43, 0, 0x18000
	s_barrier
	ds_read_b128 v[146:149], v196 offset:32768
	ds_read_b128 v[150:153], v196 offset:33792
	ds_read_b128 v[154:157], v196 offset:34816
	ds_read_b128 v[158:161], v196 offset:35840
	s_add_u32 s20, s20, 0x80000
	s_addc_u32 s21, s21, 0
	s_mov_b32 m0, s33
	ds_read_b128 v[162:165], v145 offset:32768
	ds_read_b128 v[166:169], v145 offset:33792
	ds_read_b128 v[170:173], v145 offset:34816
	ds_read_b128 v[174:177], v145 offset:35840
	ds_read_b128 v[178:181], v145 offset:36864
	ds_read_b128 v[182:185], v145 offset:37888
	ds_read_b128 v[186:189], v145 offset:38912
	ds_read_b128 v[204:207], v145 offset:39936
	global_load_lds_dwordx4 v132, s[20:21]
	s_mov_b32 m0, s34
	s_nop 0
	global_load_lds_dwordx4 v130, s[20:21]
	s_waitcnt lgkmcnt(8)
	s_barrier
	s_waitcnt lgkmcnt(0)
	v_mfma_f32_16x16x32_bf16 v[124:127], v[146:149], v[162:165], v[124:127]
	v_mfma_f32_16x16x32_bf16 v[120:123], v[154:157], v[162:165], v[120:123]
	v_mfma_f32_16x16x32_bf16 v[116:119], v[146:149], v[170:173], v[116:119]
	v_mfma_f32_16x16x32_bf16 v[108:111], v[154:157], v[170:173], v[108:111]
	v_mfma_f32_16x16x32_bf16 v[100:103], v[146:149], v[178:181], v[100:103]
	v_mfma_f32_16x16x32_bf16 v[92:95], v[154:157], v[178:181], v[92:95]
	v_mfma_f32_16x16x32_bf16 v[84:87], v[146:149], v[186:189], v[84:87]
	v_mfma_f32_16x16x32_bf16 v[76:79], v[154:157], v[186:189], v[76:79]
	v_mfma_f32_16x16x32_bf16 v[124:127], v[150:153], v[166:169], v[124:127]
	v_mfma_f32_16x16x32_bf16 v[120:123], v[158:161], v[166:169], v[120:123]
	v_mfma_f32_16x16x32_bf16 v[116:119], v[150:153], v[174:177], v[116:119]
	v_mfma_f32_16x16x32_bf16 v[108:111], v[158:161], v[174:177], v[108:111]
	v_mfma_f32_16x16x32_bf16 v[100:103], v[150:153], v[182:185], v[100:103]
	v_mfma_f32_16x16x32_bf16 v[92:95], v[158:161], v[182:185], v[92:95]
	v_mfma_f32_16x16x32_bf16 v[84:87], v[150:153], v[204:207], v[84:87]
	v_mfma_f32_16x16x32_bf16 v[76:79], v[158:161], v[204:207], v[76:79]
	s_barrier
	s_add_i32 s20, 0, 0x1c000
	s_add_i32 s21, s43, s28
	s_add_i32 m0, s21, 0xffffff80
	ds_read_b128 v[208:211], v196 offset:49152
	ds_read_b128 v[214:217], v196 offset:50176
	ds_read_b128 v[218:221], v196 offset:51200
	ds_read_b128 v[222:225], v196 offset:52224
	global_load_lds_dwordx4 v192, s[18:19] offset:128
	s_add_i32 m0, s21, 0x1f80
	s_nop 0
	global_load_lds_dwordx4 v128, s[18:19] offset:128
	s_barrier
	s_waitcnt lgkmcnt(0)
	v_mfma_f32_16x16x32_bf16 v[112:115], v[208:211], v[162:165], v[112:115]
	v_mfma_f32_16x16x32_bf16 v[104:107], v[218:221], v[162:165], v[104:107]
	v_mfma_f32_16x16x32_bf16 v[96:99], v[208:211], v[170:173], v[96:99]
	v_mfma_f32_16x16x32_bf16 v[88:91], v[218:221], v[170:173], v[88:91]
	v_mfma_f32_16x16x32_bf16 v[80:83], v[208:211], v[178:181], v[80:83]
	v_mfma_f32_16x16x32_bf16 v[72:75], v[218:221], v[178:181], v[72:75]
	v_mfma_f32_16x16x32_bf16 v[68:71], v[208:211], v[186:189], v[68:71]
	v_mfma_f32_16x16x32_bf16 v[64:67], v[218:221], v[186:189], v[64:67]
	v_mfma_f32_16x16x32_bf16 v[112:115], v[214:217], v[166:169], v[112:115]
	v_mfma_f32_16x16x32_bf16 v[104:107], v[222:225], v[166:169], v[104:107]
	v_mfma_f32_16x16x32_bf16 v[96:99], v[214:217], v[174:177], v[96:99]
	v_mfma_f32_16x16x32_bf16 v[88:91], v[222:225], v[174:177], v[88:91]
	v_mfma_f32_16x16x32_bf16 v[80:83], v[214:217], v[182:185], v[80:83]
	v_mfma_f32_16x16x32_bf16 v[72:75], v[222:225], v[182:185], v[72:75]
	v_mfma_f32_16x16x32_bf16 v[68:71], v[214:217], v[204:207], v[68:71]
	v_mfma_f32_16x16x32_bf16 v[64:67], v[222:225], v[204:207], v[64:67]
	s_mov_b32 m0, s35
	s_barrier
	ds_read_b128 v[162:165], v145 offset:49152
	ds_read_b128 v[166:169], v145 offset:50176
	ds_read_b128 v[170:173], v145 offset:51200
	ds_read_b128 v[174:177], v145 offset:52224
	ds_read_b128 v[178:181], v145 offset:53248
	ds_read_b128 v[182:185], v145 offset:54272
	ds_read_b128 v[186:189], v145 offset:55296
	ds_read_b128 v[204:207], v145 offset:56320
	global_load_lds_dwordx4 v132, s[48:49]
	s_mov_b32 m0, s36
	s_nop 0
	global_load_lds_dwordx4 v130, s[48:49]
	s_barrier
	s_waitcnt lgkmcnt(0)
	v_mfma_f32_16x16x32_bf16 v[60:63], v[146:149], v[162:165], v[60:63]
	v_mfma_f32_16x16x32_bf16 v[56:59], v[154:157], v[162:165], v[56:59]
	v_mfma_f32_16x16x32_bf16 v[52:55], v[146:149], v[170:173], v[52:55]
	v_mfma_f32_16x16x32_bf16 v[44:47], v[154:157], v[170:173], v[44:47]
	v_mfma_f32_16x16x32_bf16 v[36:39], v[146:149], v[178:181], v[36:39]
	v_mfma_f32_16x16x32_bf16 v[28:31], v[154:157], v[178:181], v[28:31]
	v_mfma_f32_16x16x32_bf16 v[20:23], v[146:149], v[186:189], v[20:23]
	v_mfma_f32_16x16x32_bf16 v[12:15], v[154:157], v[186:189], v[12:15]
	v_mfma_f32_16x16x32_bf16 v[60:63], v[150:153], v[166:169], v[60:63]
	v_mfma_f32_16x16x32_bf16 v[56:59], v[158:161], v[166:169], v[56:59]
	v_mfma_f32_16x16x32_bf16 v[52:55], v[150:153], v[174:177], v[52:55]
	v_mfma_f32_16x16x32_bf16 v[44:47], v[158:161], v[174:177], v[44:47]
	v_mfma_f32_16x16x32_bf16 v[36:39], v[150:153], v[182:185], v[36:39]
	v_mfma_f32_16x16x32_bf16 v[28:31], v[158:161], v[182:185], v[28:31]
	v_mfma_f32_16x16x32_bf16 v[20:23], v[150:153], v[204:207], v[20:23]
	v_mfma_f32_16x16x32_bf16 v[12:15], v[158:161], v[204:207], v[12:15]
	s_barrier
	s_add_u32 s18, s18, 0x80080
	s_addc_u32 s19, s19, 0
	s_add_i32 s20, s20, s28
	s_mov_b32 m0, s20
	s_nop 0
	global_load_lds_dwordx4 v192, s[18:19]
	s_add_i32 m0, s20, 0x2000
	s_nop 0
	global_load_lds_dwordx4 v128, s[18:19]
	s_waitcnt vmcnt(6)
	s_barrier
	v_mfma_f32_16x16x32_bf16 v[48:51], v[208:211], v[162:165], v[48:51]
	v_mfma_f32_16x16x32_bf16 v[40:43], v[218:221], v[162:165], v[40:43]
	v_mfma_f32_16x16x32_bf16 v[32:35], v[208:211], v[170:173], v[32:35]
	v_mfma_f32_16x16x32_bf16 v[24:27], v[218:221], v[170:173], v[24:27]
	v_mfma_f32_16x16x32_bf16 v[16:19], v[208:211], v[178:181], v[16:19]
	v_mfma_f32_16x16x32_bf16 v[8:11], v[218:221], v[178:181], v[8:11]
	v_mfma_f32_16x16x32_bf16 v[4:7], v[208:211], v[186:189], v[4:7]
	v_mfma_f32_16x16x32_bf16 v[0:3], v[218:221], v[186:189], v[0:3]
	v_mfma_f32_16x16x32_bf16 v[48:51], v[214:217], v[166:169], v[48:51]
	v_mfma_f32_16x16x32_bf16 v[40:43], v[222:225], v[166:169], v[40:43]
	v_mfma_f32_16x16x32_bf16 v[32:35], v[214:217], v[174:177], v[32:35]
	v_mfma_f32_16x16x32_bf16 v[24:27], v[222:225], v[174:177], v[24:27]
	v_mfma_f32_16x16x32_bf16 v[16:19], v[214:217], v[182:185], v[16:19]
	v_mfma_f32_16x16x32_bf16 v[8:11], v[222:225], v[182:185], v[8:11]
	v_mfma_f32_16x16x32_bf16 v[4:7], v[214:217], v[204:207], v[4:7]
	v_mfma_f32_16x16x32_bf16 v[0:3], v[222:225], v[204:207], v[0:3]
	s_add_i32 s42, s42, 2
	s_add_u32 s16, s16, 0x100
	s_addc_u32 s17, s17, 0
	s_add_u32 s40, s40, 0x100
	s_addc_u32 s41, s41, 0
	s_cmp_gt_u32 s42, 29
	s_barrier
